# v013 plus software-pipelined head-norm phase (two register sets, loads of the next row group issued before the current group's reduction)
# speedup vs baseline: 1.0036x; 1.0006x over previous
.LBB0_908:
	s_or_b64 exec, exec, s[8:9]
	s_waitcnt lgkmcnt(0)
	v_cvt_f32_u32_e32 v0, s64
	s_sub_i32 s3, 0, s64
	v_mov_b32_e32 v8, v184
	s_mov_b32 s17, 0
	v_rcp_iflag_f32_e32 v0, v0
	s_barrier
	v_mul_f32_e32 v0, 0x4f7ffffe, v0
	v_cvt_u32_f32_e32 v0, v0
	s_nop 0
	v_readfirstlane_b32 s4, v0
	s_mul_i32 s3, s3, s4
	s_mul_hi_u32 s3, s4, s3
	s_add_i32 s4, s4, s3
	s_lshr_b32 s3, s4, 18
	s_mul_i32 s4, s3, s64
	s_sub_i32 s4, 0x4000, s4
	s_add_i32 s5, s3, 1
	s_sub_i32 s6, s4, s64
	s_cmp_ge_u32 s4, s64
	s_cselect_b32 s3, s5, s3
	s_cselect_b32 s4, s6, s4
	s_add_i32 s5, s3, 1
	s_cmp_ge_u32 s4, s64
	s_cselect_b32 s3, s5, s3
	s_mul_i32 s18, s3, s2
	s_add_i32 s3, s18, s3
	s_cmp_ge_u32 s18, s3
	s_movk_i32 s4, 0x4000
	s_cbranch_scc1 .LBB0_911
	s_load_dwordx2 s[6:7], s[0:1], 0x58
	v_and_b32_e32 v0, 15, v8
	v_lshlrev_b32_e32 v9, 5, v0
	v_mbcnt_lo_u32_b32 v11, -1, 0
	v_mbcnt_hi_u32_b32 v11, -1, v11
	s_waitcnt lgkmcnt(0)
	global_load_dwordx4 v[0:3], v9, s[6:7]
	global_load_dwordx4 v[4:7], v9, s[6:7] offset:16
	v_and_b32_e32 v13, 64, v11
	v_xor_b32_e32 v12, 1, v11
	v_add_u32_e32 v13, 64, v13
	v_cmp_lt_i32_e32 vcc, v12, v13
	s_add_i32 s6, s18, 1
	s_lshl_b32 s5, s18, 5
	v_cndmask_b32_e32 v12, v11, v12, vcc
	v_lshlrev_b32_e32 v38, 2, v12
	v_xor_b32_e32 v12, 2, v11
	v_cmp_lt_i32_e32 vcc, v12, v13
	s_ashr_i32 s7, s6, 31
	s_addk_i32 s5, 0x60
	v_cndmask_b32_e32 v12, v11, v12, vcc
	v_lshlrev_b32_e32 v39, 2, v12
	v_xor_b32_e32 v12, 4, v11
	v_cmp_lt_i32_e32 vcc, v12, v13
	s_lshl_b64 s[6:7], s[6:7], 15
	s_add_u32 s20, s58, s6
	v_cndmask_b32_e32 v12, v11, v12, vcc
	v_lshlrev_b32_e32 v40, 2, v12
	v_xor_b32_e32 v12, 8, v11
	s_addc_u32 s21, s59, s7
	s_ashr_i32 s19, s18, 31
	v_ashrrev_i32_e32 v36, 4, v8
	v_bfe_u32 v37, v8, 2, 2
	v_lshlrev_b32_e32 v8, 3, v8
	v_cmp_lt_i32_e32 vcc, v12, v13
	s_lshl_b64 s[6:7], s[18:19], 15
	v_and_b32_e32 v10, 24, v8
	v_ashrrev_i32_e32 v9, 31, v8
	v_cndmask_b32_e32 v11, v11, v12, vcc
	s_add_u32 s22, s58, s6
	s_waitcnt vmcnt(3)
	v_mov_b32_e32 v25, 0
	v_lshlrev_b32_e32 v41, 2, v11
	v_lshlrev_b64 v[26:27], 1, v[8:9]
	s_addc_u32 s23, s59, s7
	v_lshlrev_b32_e32 v24, 1, v10
	s_mov_b32 s6, 0x1884a000
	s_movk_i32 s7, 0x6000
	v_mov_b32_e32 v42, 0x358637bd
	s_mov_b32 s19, 0xf800000
	v_mov_b32_e32 v43, 0x260
	s_mov_b32 s24, 0x18848000
	v_lshl_add_u64 v[12:13], s[22:23], 0, v[26:27]
	v_add_co_u32_e32 v10, vcc, s6, v12
	v_lshl_add_u64 v[8:9], s[20:21], 0, v[26:27]
	s_nop 0
	v_addc_co_u32_e32 v11, vcc, 0, v13, vcc
	v_add_co_u32_e32 v16, vcc, s6, v8
	s_ashr_i32 s9, s18, 8
	s_nop 0
	v_addc_co_u32_e32 v17, vcc, 0, v9, vcc
	v_add_co_u32_e32 v28, vcc, s24, v12
	s_add_i32 s11, s18, 1
	s_and_b32 s12, s9, 0x3fffffe0
	v_addc_co_u32_e32 v29, vcc, 0, v13, vcc
	s_add_i32 s10, s5, 0xffffffa0
	s_sub_i32 s15, s5, 64
	s_add_i32 s8, s18, 2
	s_ashr_i32 s14, s11, 8
	v_add_co_u32_e32 v30, vcc, s24, v8
	v_add_u32_e32 v18, s12, v36
	s_sub_i32 s16, s5, 32
	s_and_b32 s13, s10, 0x3ffe0
	s_and_b32 s10, s15, 0x3ffe0
	s_ashr_i32 s15, s8, 8
	v_addc_co_u32_e32 v31, vcc, 0, v9, vcc
	global_load_dwordx4 v[12:15], v[10:11], off
	s_and_b32 s12, s14, 0x3fffffe0
	global_load_dwordx4 v[8:11], v[16:17], off
	v_lshl_or_b32 v16, v18, 2, v37
	s_and_b32 s11, s16, 0x3ffe0
	s_lshl_b32 s16, s13, 1
	s_and_b32 s13, s15, 0x3fffffe0
	v_add_u32_e32 v18, s12, v36
	v_ashrrev_i32_e32 v17, 31, v16
	v_add_u32_e32 v19, s13, v36
	v_lshl_or_b32 v18, v18, 2, v37
	v_lshlrev_b64 v[16:17], 19, v[16:17]
	v_lshl_or_b32 v20, v19, 2, v37
	v_ashrrev_i32_e32 v19, 31, v18
	v_lshl_add_u64 v[16:17], s[70:71], 0, v[16:17]
	v_ashrrev_i32_e32 v21, 31, v20
	v_lshlrev_b64 v[18:19], 19, v[18:19]
	v_lshl_add_u64 v[16:17], v[16:17], 0, s[16:17]
	v_lshlrev_b64 v[20:21], 19, v[20:21]
	v_lshl_add_u64 v[18:19], s[70:71], 0, v[18:19]
	s_lshl_b32 s16, s10, 1
	v_lshl_add_u64 v[16:17], v[16:17], 0, v[24:25]
	s_ashr_i32 s9, s8, 31
	v_lshl_add_u64 v[32:33], s[70:71], 0, v[20:21]
	v_lshl_add_u64 v[18:19], v[18:19], 0, s[16:17]
	s_lshl_b32 s16, s11, 1
	global_load_dwordx4 v[20:23], v[16:17], off
	s_lshl_b64 s[8:9], s[8:9], 15
	v_lshl_add_u64 v[16:17], v[18:19], 0, v[24:25]
	v_lshl_add_u64 v[18:19], v[32:33], 0, s[16:17]
	s_add_u32 s8, s68, s8
	v_lshl_add_u64 v[34:35], v[18:19], 0, v[24:25]
	global_load_dwordx4 v[16:19], v[16:17], off
	s_addc_u32 s9, s69, s9
	s_add_i32 s10, s18, 3
	v_lshl_add_u64 v[32:33], s[8:9], 0, v[26:27]
	s_ashr_i32 s8, s10, 8
	s_and_b32 s11, s5, 0x3ffe0
	v_add_co_u32_e32 v52, vcc, s7, v32
	s_and_b32 s12, s8, 0x3fffffe0
	s_lshl_b32 s16, s11, 1
	s_ashr_i32 s11, s10, 31
	v_addc_co_u32_e32 v53, vcc, 0, v33, vcc
	global_load_dwordx4 v[44:47], v[34:35], off
	global_load_dwordx4 v[48:51], v[52:53], off
	v_add_u32_e32 v34, s12, v36
	s_lshl_b64 s[8:9], s[10:11], 15
	v_lshl_or_b32 v52, v34, 2, v37
	s_add_u32 s8, s68, s8
	v_ashrrev_i32_e32 v53, 31, v52
	v_add_co_u32_e32 v32, vcc, s4, v32
	s_addc_u32 s9, s69, s9
	v_lshlrev_b64 v[56:57], 19, v[52:53]
	v_addc_co_u32_e32 v33, vcc, 0, v33, vcc
	v_lshl_add_u64 v[34:35], s[8:9], 0, v[26:27]
	v_lshl_add_u64 v[56:57], s[70:71], 0, v[56:57]
	v_add_co_u32_e32 v52, vcc, s7, v34
	v_lshl_add_u64 v[56:57], v[56:57], 0, s[16:17]
	s_nop 0
	v_addc_co_u32_e32 v53, vcc, 0, v35, vcc
	v_lshl_add_u64 v[56:57], v[56:57], 0, v[24:25]
	global_load_dwordx4 v[52:55], v[52:53], off
	s_add_i32 s18, s18, 4
	global_load_dwordx4 v[56:59], v[56:57], off
	s_addk_i32 s5, 0x80
	s_add_u32 s20, s20, 0x20000
	s_addc_u32 s21, s21, 0
	s_add_u32 s22, s22, 0x20000
	s_addc_u32 s23, s23, 0
	s_cmp_lt_u32 s18, s3
	v_lshl_add_u64 v[116:117], s[22:23], 0, v[26:27]
	v_add_co_u32_e32 v114, vcc, s6, v116
	v_lshl_add_u64 v[112:113], s[20:21], 0, v[26:27]
	s_nop 0
	v_addc_co_u32_e32 v115, vcc, 0, v117, vcc
	v_add_co_u32_e32 v120, vcc, s6, v112
	s_ashr_i32 s9, s18, 8
	s_nop 0
	v_addc_co_u32_e32 v121, vcc, 0, v113, vcc
	v_add_co_u32_e32 v128, vcc, s24, v116
	s_add_i32 s11, s18, 1
	s_and_b32 s12, s9, 0x3fffffe0
	v_addc_co_u32_e32 v129, vcc, 0, v117, vcc
	s_add_i32 s10, s5, 0xffffffa0
	s_sub_i32 s15, s5, 64
	s_add_i32 s8, s18, 2
	s_ashr_i32 s14, s11, 8
	v_add_co_u32_e32 v130, vcc, s24, v112
	v_add_u32_e32 v122, s12, v36
	s_sub_i32 s16, s5, 32
	s_and_b32 s13, s10, 0x3ffe0
	s_and_b32 s10, s15, 0x3ffe0
	s_ashr_i32 s15, s8, 8
	v_addc_co_u32_e32 v131, vcc, 0, v113, vcc
	global_load_dwordx4 v[116:119], v[114:115], off
	s_and_b32 s12, s14, 0x3fffffe0
	global_load_dwordx4 v[112:115], v[120:121], off
	v_lshl_or_b32 v120, v122, 2, v37
	s_and_b32 s11, s16, 0x3ffe0
	s_lshl_b32 s16, s13, 1
	s_and_b32 s13, s15, 0x3fffffe0
	v_add_u32_e32 v122, s12, v36
	v_ashrrev_i32_e32 v121, 31, v120
	v_add_u32_e32 v123, s13, v36
	v_lshl_or_b32 v122, v122, 2, v37
	v_lshlrev_b64 v[120:121], 19, v[120:121]
	v_lshl_or_b32 v124, v123, 2, v37
	v_ashrrev_i32_e32 v123, 31, v122
	v_lshl_add_u64 v[120:121], s[70:71], 0, v[120:121]
	v_ashrrev_i32_e32 v125, 31, v124
	v_lshlrev_b64 v[122:123], 19, v[122:123]
	v_lshl_add_u64 v[120:121], v[120:121], 0, s[16:17]
	v_lshlrev_b64 v[124:125], 19, v[124:125]
	v_lshl_add_u64 v[122:123], s[70:71], 0, v[122:123]
	s_lshl_b32 s16, s10, 1
	v_lshl_add_u64 v[120:121], v[120:121], 0, v[24:25]
	s_ashr_i32 s9, s8, 31
	v_lshl_add_u64 v[132:133], s[70:71], 0, v[124:125]
	v_lshl_add_u64 v[122:123], v[122:123], 0, s[16:17]
	s_lshl_b32 s16, s11, 1
	global_load_dwordx4 v[124:127], v[120:121], off
	s_lshl_b64 s[8:9], s[8:9], 15
	v_lshl_add_u64 v[120:121], v[122:123], 0, v[24:25]
	v_lshl_add_u64 v[122:123], v[132:133], 0, s[16:17]
	s_add_u32 s8, s68, s8
	v_lshl_add_u64 v[134:135], v[122:123], 0, v[24:25]
	global_load_dwordx4 v[120:123], v[120:121], off
	s_addc_u32 s9, s69, s9
	s_add_i32 s10, s18, 3
	v_lshl_add_u64 v[132:133], s[8:9], 0, v[26:27]
	s_ashr_i32 s8, s10, 8
	s_and_b32 s11, s5, 0x3ffe0
	v_add_co_u32_e32 v144, vcc, s7, v132
	s_and_b32 s12, s8, 0x3fffffe0
	s_lshl_b32 s16, s11, 1
	s_ashr_i32 s11, s10, 31
	v_addc_co_u32_e32 v145, vcc, 0, v133, vcc
	global_load_dwordx4 v[136:139], v[134:135], off
	global_load_dwordx4 v[140:143], v[144:145], off
	v_add_u32_e32 v134, s12, v36
	s_lshl_b64 s[8:9], s[10:11], 15
	v_lshl_or_b32 v144, v134, 2, v37
	s_add_u32 s8, s68, s8
	v_ashrrev_i32_e32 v145, 31, v144
	v_add_co_u32_e32 v132, vcc, s4, v132
	s_addc_u32 s9, s69, s9
	v_lshlrev_b64 v[148:149], 19, v[144:145]
	v_addc_co_u32_e32 v133, vcc, 0, v133, vcc
	v_lshl_add_u64 v[134:135], s[8:9], 0, v[26:27]
	v_lshl_add_u64 v[148:149], s[70:71], 0, v[148:149]
	v_add_co_u32_e32 v144, vcc, s7, v134
	v_lshl_add_u64 v[148:149], v[148:149], 0, s[16:17]
	s_nop 0
	v_addc_co_u32_e32 v145, vcc, 0, v135, vcc
	v_lshl_add_u64 v[148:149], v[148:149], 0, v[24:25]
	global_load_dwordx4 v[144:147], v[144:145], off
	s_add_i32 s18, s18, 4
	global_load_dwordx4 v[148:151], v[148:149], off
	s_addk_i32 s5, 0x80
	s_add_u32 s20, s20, 0x20000
	s_addc_u32 s21, s21, 0
	s_add_u32 s22, s22, 0x20000
	s_addc_u32 s23, s23, 0
	s_cmp_lt_u32 s18, s3
	s_waitcnt vmcnt(15)
	v_lshlrev_b32_e32 v60, 16, v12
	v_lshlrev_b32_e32 v61, 16, v14
	s_waitcnt vmcnt(14)
	v_lshlrev_b32_e32 v68, 16, v9
	v_and_b32_e32 v70, 0xffff0000, v9
	v_lshlrev_b32_e32 v64, 16, v8
	v_and_b32_e32 v66, 0xffff0000, v8
	v_lshlrev_b32_e32 v65, 16, v10
	v_and_b32_e32 v67, 0xffff0000, v10
	v_lshlrev_b32_e32 v69, 16, v11
	v_and_b32_e32 v71, 0xffff0000, v11
	v_and_b32_e32 v12, 0xffff0000, v12
	v_and_b32_e32 v14, 0xffff0000, v14
	v_lshlrev_b32_e32 v62, 16, v13
	v_lshlrev_b32_e32 v63, 16, v15
	v_and_b32_e32 v13, 0xffff0000, v13
	v_and_b32_e32 v15, 0xffff0000, v15
	s_waitcnt vmcnt(13)
	v_and_b32_e32 v9, 0xffff0000, v20
	v_lshlrev_b32_e32 v8, 16, v20
	v_mul_f32_e32 v72, v9, v9
	v_lshlrev_b32_e32 v10, 16, v21
	v_fmac_f32_e32 v72, v8, v8
	v_and_b32_e32 v11, 0xffff0000, v21
	s_waitcnt vmcnt(12)
	v_lshlrev_b32_e32 v73, 16, v16
	v_and_b32_e32 v16, 0xffff0000, v16
	v_mul_f32_e32 v77, v16, v16
	v_fmac_f32_e32 v72, v10, v10
	v_lshlrev_b32_e32 v20, 16, v22
	v_lshlrev_b32_e32 v74, 16, v17
	v_fmac_f32_e32 v77, v73, v73
	v_fmac_f32_e32 v72, v11, v11
	v_and_b32_e32 v21, 0xffff0000, v22
	v_and_b32_e32 v17, 0xffff0000, v17
	v_fmac_f32_e32 v77, v74, v74
	v_fmac_f32_e32 v72, v20, v20
	s_waitcnt vmcnt(11)
	v_lshlrev_b32_e32 v78, 16, v44
	v_and_b32_e32 v44, 0xffff0000, v44
	v_lshlrev_b32_e32 v22, 16, v23
	v_lshlrev_b32_e32 v75, 16, v18
	v_fmac_f32_e32 v77, v17, v17
	v_mul_f32_e32 v86, v44, v44
	v_fmac_f32_e32 v72, v21, v21
	v_and_b32_e32 v23, 0xffff0000, v23
	v_and_b32_e32 v18, 0xffff0000, v18
	v_lshlrev_b32_e32 v79, 16, v45
	v_fmac_f32_e32 v77, v75, v75
	v_fmac_f32_e32 v86, v78, v78
	v_fmac_f32_e32 v72, v22, v22
	v_lshlrev_b32_e32 v76, 16, v19
	v_and_b32_e32 v45, 0xffff0000, v45
	v_fmac_f32_e32 v77, v18, v18
	v_fmac_f32_e32 v86, v79, v79
	v_fmac_f32_e32 v72, v23, v23
	v_and_b32_e32 v19, 0xffff0000, v19
	v_lshlrev_b32_e32 v80, 16, v46
	v_fmac_f32_e32 v77, v76, v76
	v_fmac_f32_e32 v86, v45, v45
	ds_bpermute_b32 v91, v38, v72
	v_and_b32_e32 v46, 0xffff0000, v46
	v_fmac_f32_e32 v77, v19, v19
	v_fmac_f32_e32 v86, v80, v80
	v_lshlrev_b32_e32 v81, 16, v47
	ds_bpermute_b32 v92, v38, v77
	v_fmac_f32_e32 v86, v46, v46
	v_and_b32_e32 v47, 0xffff0000, v47
	v_fmac_f32_e32 v86, v81, v81
	s_waitcnt vmcnt(8)
	v_lshlrev_b32_e32 v93, 16, v56
	v_and_b32_e32 v56, 0xffff0000, v56
	v_fmac_f32_e32 v86, v47, v47
	v_mul_f32_e32 v97, v56, v56
	ds_bpermute_b32 v98, v38, v86
	s_waitcnt lgkmcnt(2)
	v_add_f32_e32 v72, v72, v91
	v_lshlrev_b32_e32 v94, 16, v57
	v_fmac_f32_e32 v97, v93, v93
	ds_bpermute_b32 v91, v39, v72
	v_and_b32_e32 v57, 0xffff0000, v57
	v_fmac_f32_e32 v97, v94, v94
	s_waitcnt lgkmcnt(2)
	v_add_f32_e32 v77, v77, v92
	v_lshlrev_b32_e32 v95, 16, v58
	v_fmac_f32_e32 v97, v57, v57
	ds_bpermute_b32 v92, v39, v77
	v_and_b32_e32 v58, 0xffff0000, v58
	v_fmac_f32_e32 v97, v95, v95
	v_lshlrev_b32_e32 v96, 16, v59
	v_fmac_f32_e32 v97, v58, v58
	s_waitcnt lgkmcnt(2)
	v_add_f32_e32 v86, v86, v98
	v_and_b32_e32 v59, 0xffff0000, v59
	v_fmac_f32_e32 v97, v96, v96
	ds_bpermute_b32 v98, v39, v86
	s_waitcnt lgkmcnt(2)
	v_add_f32_e32 v72, v72, v91
	v_fmac_f32_e32 v97, v59, v59
	ds_bpermute_b32 v99, v40, v72
	ds_bpermute_b32 v91, v38, v97
	s_waitcnt lgkmcnt(3)
	v_add_f32_e32 v77, v77, v92
	ds_bpermute_b32 v92, v40, v77
	s_waitcnt lgkmcnt(3)
	v_add_f32_e32 v86, v86, v98
	ds_bpermute_b32 v98, v40, v86
	s_waitcnt lgkmcnt(3)
	v_add_f32_e32 v72, v72, v99
	s_waitcnt lgkmcnt(2)
	v_add_f32_e32 v91, v97, v91
	ds_bpermute_b32 v99, v41, v72
	ds_bpermute_b32 v97, v39, v91
	s_waitcnt lgkmcnt(3)
	v_add_f32_e32 v77, v77, v92
	ds_bpermute_b32 v92, v41, v77
	s_waitcnt lgkmcnt(3)
	v_add_f32_e32 v86, v86, v98
	ds_bpermute_b32 v98, v41, v86
	s_waitcnt lgkmcnt(3)
	v_add_f32_e32 v72, v72, v99
	s_waitcnt lgkmcnt(2)
	v_add_f32_e32 v91, v91, v97
	v_fmamk_f32 v72, v72, 0x3c000000, v42
	ds_bpermute_b32 v97, v40, v91
	s_waitcnt lgkmcnt(2)
	v_add_f32_e32 v77, v77, v92
	v_mul_f32_e32 v92, 0x4f800000, v72
	v_cmp_gt_f32_e32 vcc, s19, v72
	v_fmamk_f32 v77, v77, 0x3c000000, v42
	v_cmp_gt_f32_e64 s[8:9], s19, v77
	v_cndmask_b32_e32 v72, v72, v92, vcc
	v_mul_f32_e32 v92, 0x4f800000, v77
	v_sqrt_f32_e32 v99, v72
	v_cndmask_b32_e64 v77, v77, v92, s[8:9]
	s_waitcnt lgkmcnt(1)
	v_add_f32_e32 v86, v86, v98
	v_sqrt_f32_e32 v92, v77
	v_fmamk_f32 v86, v86, 0x3c000000, v42
	s_waitcnt lgkmcnt(0)
	v_add_f32_e32 v91, v91, v97
	v_mul_f32_e32 v97, 0x4f800000, v86
	v_cmp_gt_f32_e64 s[10:11], s19, v86
	ds_bpermute_b32 v98, v41, v91
	v_add_u32_e32 v100, 1, v99
	v_cndmask_b32_e64 v86, v86, v97, s[10:11]
	v_add_u32_e32 v97, -1, v99
	v_sqrt_f32_e32 v101, v86
	v_fma_f32 v102, -v97, v99, v72
	v_fma_f32 v103, -v100, v99, v72
	v_add_u32_e32 v104, -1, v92
	v_cmp_ge_f32_e64 s[12:13], 0, v102
	v_add_u32_e32 v105, 1, v92
	v_fma_f32 v102, -v105, v92, v77
	v_cndmask_b32_e64 v97, v99, v97, s[12:13]
	v_fma_f32 v99, -v104, v92, v77
	v_cmp_lt_f32_e64 s[12:13], 0, v103
	s_waitcnt lgkmcnt(0)
	v_add_f32_e32 v91, v91, v98
	v_fmamk_f32 v91, v91, 0x3c000000, v42
	v_cndmask_b32_e64 v97, v97, v100, s[12:13]
	v_cmp_ge_f32_e64 s[12:13], 0, v99
	v_mul_f32_e32 v98, 0x37800000, v97
	v_add_u32_e32 v99, -1, v101
	v_cndmask_b32_e64 v92, v92, v104, s[12:13]
	v_cmp_lt_f32_e64 s[12:13], 0, v102
	v_add_u32_e32 v100, 1, v101
	v_cndmask_b32_e32 v97, v97, v98, vcc
	v_cndmask_b32_e64 v92, v92, v105, s[12:13]
	v_fma_f32 v102, -v99, v101, v86
	v_cmp_class_f32_e64 s[12:13], v72, v43
	v_mul_f32_e32 v98, 0x37800000, v92
	v_fma_f32 v103, -v100, v101, v86
	v_mul_f32_e32 v104, 0x4f800000, v91
	v_cmp_gt_f32_e32 vcc, s19, v91
	v_cndmask_b32_e64 v72, v97, v72, s[12:13]
	v_cmp_ge_f32_e64 s[12:13], 0, v102
	v_cndmask_b32_e64 v92, v92, v98, s[8:9]
	v_cmp_class_f32_e64 s[8:9], v77, v43
	v_cndmask_b32_e64 v97, v101, v99, s[12:13]
	v_cmp_lt_f32_e64 s[12:13], 0, v103
	v_cndmask_b32_e32 v91, v91, v104, vcc
	v_cndmask_b32_e64 v77, v92, v77, s[8:9]
	v_cndmask_b32_e64 v92, v97, v100, s[12:13]
	v_sqrt_f32_e32 v97, v91
	v_div_scale_f32 v98, s[14:15], v72, v72, 1.0
	v_rcp_f32_e32 v100, v98
	v_div_scale_f32 v101, s[8:9], v77, v77, 1.0
	v_mul_f32_e32 v103, 0x37800000, v92
	v_rcp_f32_e32 v104, v101
	v_cndmask_b32_e64 v92, v92, v103, s[10:11]
	v_cmp_class_f32_e64 s[8:9], v86, v43
	v_add_u32_e32 v105, -1, v97
	v_add_u32_e32 v106, 1, v97
	v_cndmask_b32_e64 v86, v92, v86, s[8:9]
	v_div_scale_f32 v92, s[8:9], v86, v86, 1.0
	v_fma_f32 v109, -v105, v97, v91
	v_fma_f32 v107, -v98, v100, 1.0
	v_rcp_f32_e32 v108, v92
	v_fma_f32 v110, -v106, v97, v91
	v_cmp_ge_f32_e64 s[8:9], 0, v109
	v_div_scale_f32 v99, s[14:15], 1.0, v72, 1.0
	v_fmac_f32_e32 v100, v107, v100
	v_fma_f32 v107, -v101, v104, 1.0
	v_cndmask_b32_e64 v97, v97, v105, s[8:9]
	v_cmp_lt_f32_e64 s[8:9], 0, v110
	v_div_scale_f32 v102, s[12:13], 1.0, v77, 1.0
	v_mul_f32_e32 v105, v99, v100
	v_fmac_f32_e32 v104, v107, v104
	v_cndmask_b32_e64 v97, v97, v106, s[8:9]
	v_fma_f32 v106, -v98, v105, v99
	v_mul_f32_e32 v107, v102, v104
	v_mul_f32_e32 v109, 0x37800000, v97
	v_fmac_f32_e32 v105, v106, v100
	v_fma_f32 v106, -v101, v107, v102
	v_fma_f32 v110, -v92, v108, 1.0
	v_cndmask_b32_e32 v97, v97, v109, vcc
	v_cmp_class_f32_e32 vcc, v91, v43
	v_div_scale_f32 v103, s[10:11], 1.0, v86, 1.0
	v_fma_f32 v98, -v98, v105, v99
	v_fmac_f32_e32 v107, v106, v104
	v_fmac_f32_e32 v108, v110, v108
	v_cndmask_b32_e32 v91, v97, v91, vcc
	s_mov_b64 vcc, s[14:15]
	v_div_fmas_f32 v97, v98, v100, v105
	v_fma_f32 v98, -v101, v107, v102
	v_mul_f32_e32 v99, v103, v108
	v_div_scale_f32 v100, s[8:9], v91, v91, 1.0
	s_mov_b64 vcc, s[12:13]
	v_div_fixup_f32 v72, v97, v72, 1.0
	v_div_fmas_f32 v97, v98, v104, v107
	v_fma_f32 v98, -v92, v99, v103
	v_rcp_f32_e32 v102, v100
	v_mul_f32_e32 v8, v72, v8
	v_mul_f32_e32 v20, v72, v20
	v_mul_f32_e32 v9, v72, v9
	v_mul_f32_e32 v21, v72, v21
	v_mul_f32_e32 v10, v72, v10
	v_mul_f32_e32 v22, v72, v22
	v_mul_f32_e32 v11, v72, v11
	v_mul_f32_e32 v23, v72, v23
	v_div_fixup_f32 v72, v97, v77, 1.0
	v_fmac_f32_e32 v99, v98, v108
	v_mul_f32_e32 v8, v0, v8
	v_mul_f32_e32 v20, v4, v20
	v_mul_f32_e32 v9, v1, v9
	v_mul_f32_e32 v21, v5, v21
	v_mul_f32_e32 v10, v2, v10
	v_mul_f32_e32 v22, v6, v22
	v_mul_f32_e32 v11, v3, v11
	v_mul_f32_e32 v23, v7, v23
	v_mul_f32_e32 v73, v72, v73
	v_mul_f32_e32 v75, v72, v75
	v_mul_f32_e32 v16, v72, v16
	v_mul_f32_e32 v18, v72, v18
	v_mul_f32_e32 v74, v72, v74
	v_mul_f32_e32 v76, v72, v76
	v_mul_f32_e32 v17, v72, v17
	v_mul_f32_e32 v19, v72, v19
	v_fma_f32 v72, -v92, v99, v103
	s_mov_b64 vcc, s[10:11]
	v_mul_f32_e32 v8, v8, v60
	v_mul_f32_e32 v20, v20, v61
	v_mul_f32_e32 v9, v9, v12
	v_mul_f32_e32 v12, v21, v14
	v_mul_f32_e32 v10, v10, v62
	v_mul_f32_e32 v14, v22, v63
	v_mul_f32_e32 v11, v11, v13
	v_mul_f32_e32 v13, v23, v15
	v_mul_f32_e32 v15, v0, v73
	v_mul_f32_e32 v21, v4, v75
	v_mul_f32_e32 v16, v1, v16
	v_mul_f32_e32 v18, v5, v18
	v_mul_f32_e32 v22, v2, v74
	v_mul_f32_e32 v23, v6, v76
	v_mul_f32_e32 v17, v3, v17
	v_mul_f32_e32 v19, v7, v19
	v_div_fmas_f32 v60, v72, v108, v99
	v_cvt_pk_bf16_f32 v8, v8, v9
	v_cvt_pk_bf16_f32 v9, v10, v11
	v_cvt_pk_bf16_f32 v10, v20, v12
	v_cvt_pk_bf16_f32 v11, v14, v13
	v_mul_f32_e32 v12, v15, v64
	v_mul_f32_e32 v13, v21, v65
	v_mul_f32_e32 v14, v16, v66
	v_mul_f32_e32 v15, v18, v67
	v_mul_f32_e32 v16, v22, v68
	v_mul_f32_e32 v18, v23, v69
	v_mul_f32_e32 v17, v17, v70
	v_mul_f32_e32 v19, v19, v71
	v_div_fixup_f32 v20, v60, v86, 1.0
	v_fma_f32 v21, -v100, v102, 1.0
	v_div_scale_f32 v101, s[8:9], 1.0, v91, 1.0
	global_store_dwordx4 v[28:29], v[8:11], off
	v_fmac_f32_e32 v102, v21, v102
	v_lshlrev_b32_e32 v82, 16, v48
	v_cvt_pk_bf16_f32 v8, v12, v14
	v_cvt_pk_bf16_f32 v9, v16, v17
	v_cvt_pk_bf16_f32 v10, v13, v15
	v_cvt_pk_bf16_f32 v11, v18, v19
	v_mul_f32_e32 v12, v20, v78
	v_mul_f32_e32 v13, v20, v80
	v_mul_f32_e32 v14, v20, v44
	v_mul_f32_e32 v15, v20, v46
	v_mul_f32_e32 v16, v20, v79
	v_mul_f32_e32 v17, v20, v81
	v_mul_f32_e32 v18, v20, v45
	v_mul_f32_e32 v19, v20, v47
	v_lshlrev_b32_e32 v83, 16, v50
	v_and_b32_e32 v48, 0xffff0000, v48
	v_and_b32_e32 v50, 0xffff0000, v50
	v_lshlrev_b32_e32 v84, 16, v49
	v_lshlrev_b32_e32 v85, 16, v51
	v_and_b32_e32 v49, 0xffff0000, v49
	v_and_b32_e32 v51, 0xffff0000, v51
	global_store_dwordx4 v[30:31], v[8:11], off
	s_mov_b64 vcc, s[8:9]
	v_lshlrev_b32_e32 v87, 16, v52
	v_mul_f32_e32 v8, v0, v12
	v_mul_f32_e32 v9, v4, v13
	v_mul_f32_e32 v10, v1, v14
	v_mul_f32_e32 v11, v5, v15
	v_mul_f32_e32 v12, v2, v16
	v_mul_f32_e32 v13, v6, v17
	v_mul_f32_e32 v14, v3, v18
	v_mul_f32_e32 v15, v7, v19
	v_mul_f32_e32 v16, v101, v102
	v_mul_f32_e32 v8, v8, v82
	v_mul_f32_e32 v17, v9, v83
	v_mul_f32_e32 v9, v10, v48
	v_mul_f32_e32 v10, v11, v50
	v_mul_f32_e32 v11, v12, v84
	v_mul_f32_e32 v12, v13, v85
	v_mul_f32_e32 v13, v14, v49
	v_mul_f32_e32 v14, v15, v51
	v_fma_f32 v15, -v100, v16, v101
	v_cvt_pk_bf16_f32 v8, v8, v9
	v_fmac_f32_e32 v16, v15, v102
	v_cvt_pk_bf16_f32 v9, v11, v13
	v_cvt_pk_bf16_f32 v10, v17, v10
	v_cvt_pk_bf16_f32 v11, v12, v14
	global_store_dwordx4 v[32:33], v[8:11], off
	v_lshlrev_b32_e32 v88, 16, v54
	v_and_b32_e32 v52, 0xffff0000, v52
	v_fma_f32 v8, -v100, v16, v101
	v_div_fmas_f32 v8, v8, v102, v16
	v_div_fixup_f32 v8, v8, v91, 1.0
	v_mul_f32_e32 v9, v8, v93
	v_mul_f32_e32 v10, v8, v95
	v_mul_f32_e32 v11, v8, v56
	v_add_co_u32_e32 v12, vcc, s4, v34
	v_mul_f32_e32 v14, v8, v58
	v_mul_f32_e32 v15, v8, v94
	v_mul_f32_e32 v16, v8, v96
	v_mul_f32_e32 v17, v8, v57
	v_mul_f32_e32 v8, v8, v59
	v_mul_f32_e32 v9, v0, v9
	v_mul_f32_e32 v10, v4, v10
	v_mul_f32_e32 v11, v1, v11
	v_and_b32_e32 v54, 0xffff0000, v54
	v_lshlrev_b32_e32 v89, 16, v53
	v_lshlrev_b32_e32 v90, 16, v55
	v_and_b32_e32 v53, 0xffff0000, v53
	v_and_b32_e32 v55, 0xffff0000, v55
	v_addc_co_u32_e32 v13, vcc, 0, v35, vcc
	v_mul_f32_e32 v14, v5, v14
	v_mul_f32_e32 v15, v2, v15
	v_mul_f32_e32 v16, v6, v16
	v_mul_f32_e32 v17, v3, v17
	v_mul_f32_e32 v8, v7, v8
	v_mul_f32_e32 v9, v9, v87
	v_mul_f32_e32 v10, v10, v88
	v_mul_f32_e32 v11, v11, v52
	v_mul_f32_e32 v14, v14, v54
	v_mul_f32_e32 v15, v15, v89
	v_mul_f32_e32 v16, v16, v90
	v_mul_f32_e32 v17, v17, v53
	v_mul_f32_e32 v18, v8, v55
	v_cvt_pk_bf16_f32 v8, v9, v11
	v_cvt_pk_bf16_f32 v9, v15, v17
	v_cvt_pk_bf16_f32 v10, v10, v14
	v_cvt_pk_bf16_f32 v11, v16, v18
	global_store_dwordx4 v[12:13], v[8:11], off
	s_nop 1
	v_lshl_add_u64 v[12:13], s[22:23], 0, v[26:27]
	v_add_co_u32_e32 v10, vcc, s6, v12
	v_lshl_add_u64 v[8:9], s[20:21], 0, v[26:27]
	s_nop 0
	v_addc_co_u32_e32 v11, vcc, 0, v13, vcc
	v_add_co_u32_e32 v16, vcc, s6, v8
	s_ashr_i32 s9, s18, 8
	s_nop 0
	v_addc_co_u32_e32 v17, vcc, 0, v9, vcc
	v_add_co_u32_e32 v28, vcc, s24, v12
	s_add_i32 s11, s18, 1
	s_and_b32 s12, s9, 0x3fffffe0
	v_addc_co_u32_e32 v29, vcc, 0, v13, vcc
	s_add_i32 s10, s5, 0xffffffa0
	s_sub_i32 s15, s5, 64
	s_add_i32 s8, s18, 2
	s_ashr_i32 s14, s11, 8
	v_add_co_u32_e32 v30, vcc, s24, v8
	v_add_u32_e32 v18, s12, v36
	s_sub_i32 s16, s5, 32
	s_and_b32 s13, s10, 0x3ffe0
	s_and_b32 s10, s15, 0x3ffe0
	s_ashr_i32 s15, s8, 8
	v_addc_co_u32_e32 v31, vcc, 0, v9, vcc
	global_load_dwordx4 v[12:15], v[10:11], off
	s_and_b32 s12, s14, 0x3fffffe0
	global_load_dwordx4 v[8:11], v[16:17], off
	v_lshl_or_b32 v16, v18, 2, v37
	s_and_b32 s11, s16, 0x3ffe0
	s_lshl_b32 s16, s13, 1
	s_and_b32 s13, s15, 0x3fffffe0
	v_add_u32_e32 v18, s12, v36
	v_ashrrev_i32_e32 v17, 31, v16
	v_add_u32_e32 v19, s13, v36
	v_lshl_or_b32 v18, v18, 2, v37
	v_lshlrev_b64 v[16:17], 19, v[16:17]
	v_lshl_or_b32 v20, v19, 2, v37
	v_ashrrev_i32_e32 v19, 31, v18
	v_lshl_add_u64 v[16:17], s[70:71], 0, v[16:17]
	v_ashrrev_i32_e32 v21, 31, v20
	v_lshlrev_b64 v[18:19], 19, v[18:19]
	v_lshl_add_u64 v[16:17], v[16:17], 0, s[16:17]
	v_lshlrev_b64 v[20:21], 19, v[20:21]
	v_lshl_add_u64 v[18:19], s[70:71], 0, v[18:19]
	s_lshl_b32 s16, s10, 1
	v_lshl_add_u64 v[16:17], v[16:17], 0, v[24:25]
	s_ashr_i32 s9, s8, 31
	v_lshl_add_u64 v[32:33], s[70:71], 0, v[20:21]
	v_lshl_add_u64 v[18:19], v[18:19], 0, s[16:17]
	s_lshl_b32 s16, s11, 1
	global_load_dwordx4 v[20:23], v[16:17], off
	s_lshl_b64 s[8:9], s[8:9], 15
	v_lshl_add_u64 v[16:17], v[18:19], 0, v[24:25]
	v_lshl_add_u64 v[18:19], v[32:33], 0, s[16:17]
	s_add_u32 s8, s68, s8
	v_lshl_add_u64 v[34:35], v[18:19], 0, v[24:25]
	global_load_dwordx4 v[16:19], v[16:17], off
	s_addc_u32 s9, s69, s9
	s_add_i32 s10, s18, 3
	v_lshl_add_u64 v[32:33], s[8:9], 0, v[26:27]
	s_ashr_i32 s8, s10, 8
	s_and_b32 s11, s5, 0x3ffe0
	v_add_co_u32_e32 v52, vcc, s7, v32
	s_and_b32 s12, s8, 0x3fffffe0
	s_lshl_b32 s16, s11, 1
	s_ashr_i32 s11, s10, 31
	v_addc_co_u32_e32 v53, vcc, 0, v33, vcc
	global_load_dwordx4 v[44:47], v[34:35], off
	global_load_dwordx4 v[48:51], v[52:53], off
	v_add_u32_e32 v34, s12, v36
	s_lshl_b64 s[8:9], s[10:11], 15
	v_lshl_or_b32 v52, v34, 2, v37
	s_add_u32 s8, s68, s8
	v_ashrrev_i32_e32 v53, 31, v52
	v_add_co_u32_e32 v32, vcc, s4, v32
	s_addc_u32 s9, s69, s9
	v_lshlrev_b64 v[56:57], 19, v[52:53]
	v_addc_co_u32_e32 v33, vcc, 0, v33, vcc
	v_lshl_add_u64 v[34:35], s[8:9], 0, v[26:27]
	v_lshl_add_u64 v[56:57], s[70:71], 0, v[56:57]
	v_add_co_u32_e32 v52, vcc, s7, v34
	v_lshl_add_u64 v[56:57], v[56:57], 0, s[16:17]
	s_nop 0
	v_addc_co_u32_e32 v53, vcc, 0, v35, vcc
	v_lshl_add_u64 v[56:57], v[56:57], 0, v[24:25]
	global_load_dwordx4 v[52:55], v[52:53], off
	s_add_i32 s18, s18, 4
	global_load_dwordx4 v[56:59], v[56:57], off
	s_addk_i32 s5, 0x80
	s_add_u32 s20, s20, 0x20000
	s_addc_u32 s21, s21, 0
	s_add_u32 s22, s22, 0x20000
	s_addc_u32 s23, s23, 0
	s_cmp_lt_u32 s18, s3
	s_mov_b32 s98, 6
.Lhn_loop:
	s_waitcnt vmcnt(19)
	v_lshlrev_b32_e32 v152, 16, v116
	v_lshlrev_b32_e32 v153, 16, v118
	s_waitcnt vmcnt(18)
	v_lshlrev_b32_e32 v160, 16, v113
	v_and_b32_e32 v162, 0xffff0000, v113
	v_lshlrev_b32_e32 v156, 16, v112
	v_and_b32_e32 v158, 0xffff0000, v112
	v_lshlrev_b32_e32 v157, 16, v114
	v_and_b32_e32 v159, 0xffff0000, v114
	v_lshlrev_b32_e32 v161, 16, v115
	v_and_b32_e32 v163, 0xffff0000, v115
	v_and_b32_e32 v116, 0xffff0000, v116
	v_and_b32_e32 v118, 0xffff0000, v118
	v_lshlrev_b32_e32 v154, 16, v117
	v_lshlrev_b32_e32 v155, 16, v119
	v_and_b32_e32 v117, 0xffff0000, v117
	v_and_b32_e32 v119, 0xffff0000, v119
	s_waitcnt vmcnt(17)
	v_and_b32_e32 v113, 0xffff0000, v124
	v_lshlrev_b32_e32 v112, 16, v124
	v_mul_f32_e32 v164, v113, v113
	v_lshlrev_b32_e32 v114, 16, v125
	v_fmac_f32_e32 v164, v112, v112
	v_and_b32_e32 v115, 0xffff0000, v125
	s_waitcnt vmcnt(16)
	v_lshlrev_b32_e32 v165, 16, v120
	v_and_b32_e32 v120, 0xffff0000, v120
	v_mul_f32_e32 v169, v120, v120
	v_fmac_f32_e32 v164, v114, v114
	v_lshlrev_b32_e32 v124, 16, v126
	v_lshlrev_b32_e32 v166, 16, v121
	v_fmac_f32_e32 v169, v165, v165
	v_fmac_f32_e32 v164, v115, v115
	v_and_b32_e32 v125, 0xffff0000, v126
	v_and_b32_e32 v121, 0xffff0000, v121
	v_fmac_f32_e32 v169, v166, v166
	v_fmac_f32_e32 v164, v124, v124
	s_waitcnt vmcnt(15)
	v_lshlrev_b32_e32 v170, 16, v136
	v_and_b32_e32 v136, 0xffff0000, v136
	v_lshlrev_b32_e32 v126, 16, v127
	v_lshlrev_b32_e32 v167, 16, v122
	v_fmac_f32_e32 v169, v121, v121
	v_mul_f32_e32 v192, v136, v136
	v_fmac_f32_e32 v164, v125, v125
	v_and_b32_e32 v127, 0xffff0000, v127
	v_and_b32_e32 v122, 0xffff0000, v122
	v_lshlrev_b32_e32 v171, 16, v137
	v_fmac_f32_e32 v169, v167, v167
	v_fmac_f32_e32 v192, v170, v170
	v_fmac_f32_e32 v164, v126, v126
	v_lshlrev_b32_e32 v168, 16, v123
	v_and_b32_e32 v137, 0xffff0000, v137
	v_fmac_f32_e32 v169, v122, v122
	v_fmac_f32_e32 v192, v171, v171
	v_fmac_f32_e32 v164, v127, v127
	v_and_b32_e32 v123, 0xffff0000, v123
	v_lshlrev_b32_e32 v186, 16, v138
	v_fmac_f32_e32 v169, v168, v168
	v_fmac_f32_e32 v192, v137, v137
	ds_bpermute_b32 v197, v38, v164
	v_and_b32_e32 v138, 0xffff0000, v138
	v_fmac_f32_e32 v169, v123, v123
	v_fmac_f32_e32 v192, v186, v186
	v_lshlrev_b32_e32 v187, 16, v139
	ds_bpermute_b32 v198, v38, v169
	v_fmac_f32_e32 v192, v138, v138
	v_and_b32_e32 v139, 0xffff0000, v139
	v_fmac_f32_e32 v192, v187, v187
	s_waitcnt vmcnt(12)
	v_lshlrev_b32_e32 v199, 16, v148
	v_and_b32_e32 v148, 0xffff0000, v148
	v_fmac_f32_e32 v192, v139, v139
	v_mul_f32_e32 v203, v148, v148
	ds_bpermute_b32 v204, v38, v192
	s_waitcnt lgkmcnt(2)
	v_add_f32_e32 v164, v164, v197
	v_lshlrev_b32_e32 v200, 16, v149
	v_fmac_f32_e32 v203, v199, v199
	ds_bpermute_b32 v197, v39, v164
	v_and_b32_e32 v149, 0xffff0000, v149
	v_fmac_f32_e32 v203, v200, v200
	s_waitcnt lgkmcnt(2)
	v_add_f32_e32 v169, v169, v198
	v_lshlrev_b32_e32 v201, 16, v150
	v_fmac_f32_e32 v203, v149, v149
	ds_bpermute_b32 v198, v39, v169
	v_and_b32_e32 v150, 0xffff0000, v150
	v_fmac_f32_e32 v203, v201, v201
	v_lshlrev_b32_e32 v202, 16, v151
	v_fmac_f32_e32 v203, v150, v150
	s_waitcnt lgkmcnt(2)
	v_add_f32_e32 v192, v192, v204
	v_and_b32_e32 v151, 0xffff0000, v151
	v_fmac_f32_e32 v203, v202, v202
	ds_bpermute_b32 v204, v39, v192
	s_waitcnt lgkmcnt(2)
	v_add_f32_e32 v164, v164, v197
	v_fmac_f32_e32 v203, v151, v151
	ds_bpermute_b32 v205, v40, v164
	ds_bpermute_b32 v197, v38, v203
	s_waitcnt lgkmcnt(3)
	v_add_f32_e32 v169, v169, v198
	ds_bpermute_b32 v198, v40, v169
	s_waitcnt lgkmcnt(3)
	v_add_f32_e32 v192, v192, v204
	ds_bpermute_b32 v204, v40, v192
	s_waitcnt lgkmcnt(3)
	v_add_f32_e32 v164, v164, v205
	s_waitcnt lgkmcnt(2)
	v_add_f32_e32 v197, v203, v197
	ds_bpermute_b32 v205, v41, v164
	ds_bpermute_b32 v203, v39, v197
	s_waitcnt lgkmcnt(3)
	v_add_f32_e32 v169, v169, v198
	ds_bpermute_b32 v198, v41, v169
	s_waitcnt lgkmcnt(3)
	v_add_f32_e32 v192, v192, v204
	ds_bpermute_b32 v204, v41, v192
	s_waitcnt lgkmcnt(3)
	v_add_f32_e32 v164, v164, v205
	s_waitcnt lgkmcnt(2)
	v_add_f32_e32 v197, v197, v203
	v_fmamk_f32 v164, v164, 0x3c000000, v42
	ds_bpermute_b32 v203, v40, v197
	s_waitcnt lgkmcnt(2)
	v_add_f32_e32 v169, v169, v198
	v_mul_f32_e32 v198, 0x4f800000, v164
	v_cmp_gt_f32_e32 vcc, s19, v164
	v_fmamk_f32 v169, v169, 0x3c000000, v42
	v_cmp_gt_f32_e64 s[8:9], s19, v169
	v_cndmask_b32_e32 v164, v164, v198, vcc
	v_mul_f32_e32 v198, 0x4f800000, v169
	v_sqrt_f32_e32 v205, v164
	v_cndmask_b32_e64 v169, v169, v198, s[8:9]
	s_waitcnt lgkmcnt(1)
	v_add_f32_e32 v192, v192, v204
	v_sqrt_f32_e32 v198, v169
	v_fmamk_f32 v192, v192, 0x3c000000, v42
	s_waitcnt lgkmcnt(0)
	v_add_f32_e32 v197, v197, v203
	v_mul_f32_e32 v203, 0x4f800000, v192
	v_cmp_gt_f32_e64 s[10:11], s19, v192
	ds_bpermute_b32 v204, v41, v197
	v_add_u32_e32 v206, 1, v205
	v_cndmask_b32_e64 v192, v192, v203, s[10:11]
	v_add_u32_e32 v203, -1, v205
	v_sqrt_f32_e32 v207, v192
	v_fma_f32 v208, -v203, v205, v164
	v_fma_f32 v209, -v206, v205, v164
	v_add_u32_e32 v210, -1, v198
	v_cmp_ge_f32_e64 s[12:13], 0, v208
	v_add_u32_e32 v211, 1, v198
	v_fma_f32 v208, -v211, v198, v169
	v_cndmask_b32_e64 v203, v205, v203, s[12:13]
	v_fma_f32 v205, -v210, v198, v169
	v_cmp_lt_f32_e64 s[12:13], 0, v209
	s_waitcnt lgkmcnt(0)
	v_add_f32_e32 v197, v197, v204
	v_fmamk_f32 v197, v197, 0x3c000000, v42
	v_cndmask_b32_e64 v203, v203, v206, s[12:13]
	v_cmp_ge_f32_e64 s[12:13], 0, v205
	v_mul_f32_e32 v204, 0x37800000, v203
	v_add_u32_e32 v205, -1, v207
	v_cndmask_b32_e64 v198, v198, v210, s[12:13]
	v_cmp_lt_f32_e64 s[12:13], 0, v208
	v_add_u32_e32 v206, 1, v207
	v_cndmask_b32_e32 v203, v203, v204, vcc
	v_cndmask_b32_e64 v198, v198, v211, s[12:13]
	v_fma_f32 v208, -v205, v207, v192
	v_cmp_class_f32_e64 s[12:13], v164, v43
	v_mul_f32_e32 v204, 0x37800000, v198
	v_fma_f32 v209, -v206, v207, v192
	v_mul_f32_e32 v210, 0x4f800000, v197
	v_cmp_gt_f32_e32 vcc, s19, v197
	v_cndmask_b32_e64 v164, v203, v164, s[12:13]
	v_cmp_ge_f32_e64 s[12:13], 0, v208
	v_cndmask_b32_e64 v198, v198, v204, s[8:9]
	v_cmp_class_f32_e64 s[8:9], v169, v43
	v_cndmask_b32_e64 v203, v207, v205, s[12:13]
	v_cmp_lt_f32_e64 s[12:13], 0, v209
	v_cndmask_b32_e32 v197, v197, v210, vcc
	v_cndmask_b32_e64 v169, v198, v169, s[8:9]
	v_cndmask_b32_e64 v198, v203, v206, s[12:13]
	v_sqrt_f32_e32 v203, v197
	v_div_scale_f32 v204, s[14:15], v164, v164, 1.0
	v_rcp_f32_e32 v206, v204
	v_div_scale_f32 v207, s[8:9], v169, v169, 1.0
	v_mul_f32_e32 v209, 0x37800000, v198
	v_rcp_f32_e32 v210, v207
	v_cndmask_b32_e64 v198, v198, v209, s[10:11]
	v_cmp_class_f32_e64 s[8:9], v192, v43
	v_add_u32_e32 v211, -1, v203
	v_add_u32_e32 v212, 1, v203
	v_cndmask_b32_e64 v192, v198, v192, s[8:9]
	v_div_scale_f32 v198, s[8:9], v192, v192, 1.0
	v_fma_f32 v215, -v211, v203, v197
	v_fma_f32 v213, -v204, v206, 1.0
	v_rcp_f32_e32 v214, v198
	v_fma_f32 v216, -v212, v203, v197
	v_cmp_ge_f32_e64 s[8:9], 0, v215
	v_div_scale_f32 v205, s[14:15], 1.0, v164, 1.0
	v_fmac_f32_e32 v206, v213, v206
	v_fma_f32 v213, -v207, v210, 1.0
	v_cndmask_b32_e64 v203, v203, v211, s[8:9]
	v_cmp_lt_f32_e64 s[8:9], 0, v216
	v_div_scale_f32 v208, s[12:13], 1.0, v169, 1.0
	v_mul_f32_e32 v211, v205, v206
	v_fmac_f32_e32 v210, v213, v210
	v_cndmask_b32_e64 v203, v203, v212, s[8:9]
	v_fma_f32 v212, -v204, v211, v205
	v_mul_f32_e32 v213, v208, v210
	v_mul_f32_e32 v215, 0x37800000, v203
	v_fmac_f32_e32 v211, v212, v206
	v_fma_f32 v212, -v207, v213, v208
	v_fma_f32 v216, -v198, v214, 1.0
	v_cndmask_b32_e32 v203, v203, v215, vcc
	v_cmp_class_f32_e32 vcc, v197, v43
	v_div_scale_f32 v209, s[10:11], 1.0, v192, 1.0
	v_fma_f32 v204, -v204, v211, v205
	v_fmac_f32_e32 v213, v212, v210
	v_fmac_f32_e32 v214, v216, v214
	v_cndmask_b32_e32 v197, v203, v197, vcc
	s_mov_b64 vcc, s[14:15]
	v_div_fmas_f32 v203, v204, v206, v211
	v_fma_f32 v204, -v207, v213, v208
	v_mul_f32_e32 v205, v209, v214
	v_div_scale_f32 v206, s[8:9], v197, v197, 1.0
	s_mov_b64 vcc, s[12:13]
	v_div_fixup_f32 v164, v203, v164, 1.0
	v_div_fmas_f32 v203, v204, v210, v213
	v_fma_f32 v204, -v198, v205, v209
	v_rcp_f32_e32 v208, v206
	v_mul_f32_e32 v112, v164, v112
	v_mul_f32_e32 v124, v164, v124
	v_mul_f32_e32 v113, v164, v113
	v_mul_f32_e32 v125, v164, v125
	v_mul_f32_e32 v114, v164, v114
	v_mul_f32_e32 v126, v164, v126
	v_mul_f32_e32 v115, v164, v115
	v_mul_f32_e32 v127, v164, v127
	v_div_fixup_f32 v164, v203, v169, 1.0
	v_fmac_f32_e32 v205, v204, v214
	v_mul_f32_e32 v112, v0, v112
	v_mul_f32_e32 v124, v4, v124
	v_mul_f32_e32 v113, v1, v113
	v_mul_f32_e32 v125, v5, v125
	v_mul_f32_e32 v114, v2, v114
	v_mul_f32_e32 v126, v6, v126
	v_mul_f32_e32 v115, v3, v115
	v_mul_f32_e32 v127, v7, v127
	v_mul_f32_e32 v165, v164, v165
	v_mul_f32_e32 v167, v164, v167
	v_mul_f32_e32 v120, v164, v120
	v_mul_f32_e32 v122, v164, v122
	v_mul_f32_e32 v166, v164, v166
	v_mul_f32_e32 v168, v164, v168
	v_mul_f32_e32 v121, v164, v121
	v_mul_f32_e32 v123, v164, v123
	v_fma_f32 v164, -v198, v205, v209
	s_mov_b64 vcc, s[10:11]
	v_mul_f32_e32 v112, v112, v152
	v_mul_f32_e32 v124, v124, v153
	v_mul_f32_e32 v113, v113, v116
	v_mul_f32_e32 v116, v125, v118
	v_mul_f32_e32 v114, v114, v154
	v_mul_f32_e32 v118, v126, v155
	v_mul_f32_e32 v115, v115, v117
	v_mul_f32_e32 v117, v127, v119
	v_mul_f32_e32 v119, v0, v165
	v_mul_f32_e32 v125, v4, v167
	v_mul_f32_e32 v120, v1, v120
	v_mul_f32_e32 v122, v5, v122
	v_mul_f32_e32 v126, v2, v166
	v_mul_f32_e32 v127, v6, v168
	v_mul_f32_e32 v121, v3, v121
	v_mul_f32_e32 v123, v7, v123
	v_div_fmas_f32 v152, v164, v214, v205
	v_cvt_pk_bf16_f32 v112, v112, v113
	v_cvt_pk_bf16_f32 v113, v114, v115
	v_cvt_pk_bf16_f32 v114, v124, v116
	v_cvt_pk_bf16_f32 v115, v118, v117
	v_mul_f32_e32 v116, v119, v156
	v_mul_f32_e32 v117, v125, v157
	v_mul_f32_e32 v118, v120, v158
	v_mul_f32_e32 v119, v122, v159
	v_mul_f32_e32 v120, v126, v160
	v_mul_f32_e32 v122, v127, v161
	v_mul_f32_e32 v121, v121, v162
	v_mul_f32_e32 v123, v123, v163
	v_div_fixup_f32 v124, v152, v192, 1.0
	v_fma_f32 v125, -v206, v208, 1.0
	v_div_scale_f32 v207, s[8:9], 1.0, v197, 1.0
	global_store_dwordx4 v[128:129], v[112:115], off
	v_fmac_f32_e32 v208, v125, v208
	v_lshlrev_b32_e32 v188, 16, v140
	v_cvt_pk_bf16_f32 v112, v116, v118
	v_cvt_pk_bf16_f32 v113, v120, v121
	v_cvt_pk_bf16_f32 v114, v117, v119
	v_cvt_pk_bf16_f32 v115, v122, v123
	v_mul_f32_e32 v116, v124, v170
	v_mul_f32_e32 v117, v124, v186
	v_mul_f32_e32 v118, v124, v136
	v_mul_f32_e32 v119, v124, v138
	v_mul_f32_e32 v120, v124, v171
	v_mul_f32_e32 v121, v124, v187
	v_mul_f32_e32 v122, v124, v137
	v_mul_f32_e32 v123, v124, v139
	v_lshlrev_b32_e32 v189, 16, v142
	v_and_b32_e32 v140, 0xffff0000, v140
	v_and_b32_e32 v142, 0xffff0000, v142
	v_lshlrev_b32_e32 v190, 16, v141
	v_lshlrev_b32_e32 v191, 16, v143
	v_and_b32_e32 v141, 0xffff0000, v141
	v_and_b32_e32 v143, 0xffff0000, v143
	global_store_dwordx4 v[130:131], v[112:115], off
	s_mov_b64 vcc, s[8:9]
	v_lshlrev_b32_e32 v193, 16, v144
	v_mul_f32_e32 v112, v0, v116
	v_mul_f32_e32 v113, v4, v117
	v_mul_f32_e32 v114, v1, v118
	v_mul_f32_e32 v115, v5, v119
	v_mul_f32_e32 v116, v2, v120
	v_mul_f32_e32 v117, v6, v121
	v_mul_f32_e32 v118, v3, v122
	v_mul_f32_e32 v119, v7, v123
	v_mul_f32_e32 v120, v207, v208
	v_mul_f32_e32 v112, v112, v188
	v_mul_f32_e32 v121, v113, v189
	v_mul_f32_e32 v113, v114, v140
	v_mul_f32_e32 v114, v115, v142
	v_mul_f32_e32 v115, v116, v190
	v_mul_f32_e32 v116, v117, v191
	v_mul_f32_e32 v117, v118, v141
	v_mul_f32_e32 v118, v119, v143
	v_fma_f32 v119, -v206, v120, v207
	v_cvt_pk_bf16_f32 v112, v112, v113
	v_fmac_f32_e32 v120, v119, v208
	v_cvt_pk_bf16_f32 v113, v115, v117
	v_cvt_pk_bf16_f32 v114, v121, v114
	v_cvt_pk_bf16_f32 v115, v116, v118
	global_store_dwordx4 v[132:133], v[112:115], off
	v_lshlrev_b32_e32 v194, 16, v146
	v_and_b32_e32 v144, 0xffff0000, v144
	v_fma_f32 v112, -v206, v120, v207
	v_div_fmas_f32 v112, v112, v208, v120
	v_div_fixup_f32 v112, v112, v197, 1.0
	v_mul_f32_e32 v113, v112, v199
	v_mul_f32_e32 v114, v112, v201
	v_mul_f32_e32 v115, v112, v148
	v_add_co_u32_e32 v116, vcc, s4, v134
	v_mul_f32_e32 v118, v112, v150
	v_mul_f32_e32 v119, v112, v200
	v_mul_f32_e32 v120, v112, v202
	v_mul_f32_e32 v121, v112, v149
	v_mul_f32_e32 v112, v112, v151
	v_mul_f32_e32 v113, v0, v113
	v_mul_f32_e32 v114, v4, v114
	v_mul_f32_e32 v115, v1, v115
	v_and_b32_e32 v146, 0xffff0000, v146
	v_lshlrev_b32_e32 v195, 16, v145
	v_lshlrev_b32_e32 v196, 16, v147
	v_and_b32_e32 v145, 0xffff0000, v145
	v_and_b32_e32 v147, 0xffff0000, v147
	v_addc_co_u32_e32 v117, vcc, 0, v135, vcc
	v_mul_f32_e32 v118, v5, v118
	v_mul_f32_e32 v119, v2, v119
	v_mul_f32_e32 v120, v6, v120
	v_mul_f32_e32 v121, v3, v121
	v_mul_f32_e32 v112, v7, v112
	v_mul_f32_e32 v113, v113, v193
	v_mul_f32_e32 v114, v114, v194
	v_mul_f32_e32 v115, v115, v144
	v_mul_f32_e32 v118, v118, v146
	v_mul_f32_e32 v119, v119, v195
	v_mul_f32_e32 v120, v120, v196
	v_mul_f32_e32 v121, v121, v145
	v_mul_f32_e32 v122, v112, v147
	v_cvt_pk_bf16_f32 v112, v113, v115
	v_cvt_pk_bf16_f32 v113, v119, v121
	v_cvt_pk_bf16_f32 v114, v114, v118
	v_cvt_pk_bf16_f32 v115, v120, v122
	global_store_dwordx4 v[116:117], v[112:115], off
	s_nop 1
	v_lshl_add_u64 v[116:117], s[22:23], 0, v[26:27]
	v_add_co_u32_e32 v114, vcc, s6, v116
	v_lshl_add_u64 v[112:113], s[20:21], 0, v[26:27]
	s_nop 0
	v_addc_co_u32_e32 v115, vcc, 0, v117, vcc
	v_add_co_u32_e32 v120, vcc, s6, v112
	s_ashr_i32 s9, s18, 8
	s_nop 0
	v_addc_co_u32_e32 v121, vcc, 0, v113, vcc
	v_add_co_u32_e32 v128, vcc, s24, v116
	s_add_i32 s11, s18, 1
	s_and_b32 s12, s9, 0x3fffffe0
	v_addc_co_u32_e32 v129, vcc, 0, v117, vcc
	s_add_i32 s10, s5, 0xffffffa0
	s_sub_i32 s15, s5, 64
	s_add_i32 s8, s18, 2
	s_ashr_i32 s14, s11, 8
	v_add_co_u32_e32 v130, vcc, s24, v112
	v_add_u32_e32 v122, s12, v36
	s_sub_i32 s16, s5, 32
	s_and_b32 s13, s10, 0x3ffe0
	s_and_b32 s10, s15, 0x3ffe0
	s_ashr_i32 s15, s8, 8
	v_addc_co_u32_e32 v131, vcc, 0, v113, vcc
	global_load_dwordx4 v[116:119], v[114:115], off
	s_and_b32 s12, s14, 0x3fffffe0
	global_load_dwordx4 v[112:115], v[120:121], off
	v_lshl_or_b32 v120, v122, 2, v37
	s_and_b32 s11, s16, 0x3ffe0
	s_lshl_b32 s16, s13, 1
	s_and_b32 s13, s15, 0x3fffffe0
	v_add_u32_e32 v122, s12, v36
	v_ashrrev_i32_e32 v121, 31, v120
	v_add_u32_e32 v123, s13, v36
	v_lshl_or_b32 v122, v122, 2, v37
	v_lshlrev_b64 v[120:121], 19, v[120:121]
	v_lshl_or_b32 v124, v123, 2, v37
	v_ashrrev_i32_e32 v123, 31, v122
	v_lshl_add_u64 v[120:121], s[70:71], 0, v[120:121]
	v_ashrrev_i32_e32 v125, 31, v124
	v_lshlrev_b64 v[122:123], 19, v[122:123]
	v_lshl_add_u64 v[120:121], v[120:121], 0, s[16:17]
	v_lshlrev_b64 v[124:125], 19, v[124:125]
	v_lshl_add_u64 v[122:123], s[70:71], 0, v[122:123]
	s_lshl_b32 s16, s10, 1
	v_lshl_add_u64 v[120:121], v[120:121], 0, v[24:25]
	s_ashr_i32 s9, s8, 31
	v_lshl_add_u64 v[132:133], s[70:71], 0, v[124:125]
	v_lshl_add_u64 v[122:123], v[122:123], 0, s[16:17]
	s_lshl_b32 s16, s11, 1
	global_load_dwordx4 v[124:127], v[120:121], off
	s_lshl_b64 s[8:9], s[8:9], 15
	v_lshl_add_u64 v[120:121], v[122:123], 0, v[24:25]
	v_lshl_add_u64 v[122:123], v[132:133], 0, s[16:17]
	s_add_u32 s8, s68, s8
	v_lshl_add_u64 v[134:135], v[122:123], 0, v[24:25]
	global_load_dwordx4 v[120:123], v[120:121], off
	s_addc_u32 s9, s69, s9
	s_add_i32 s10, s18, 3
	v_lshl_add_u64 v[132:133], s[8:9], 0, v[26:27]
	s_ashr_i32 s8, s10, 8
	s_and_b32 s11, s5, 0x3ffe0
	v_add_co_u32_e32 v144, vcc, s7, v132
	s_and_b32 s12, s8, 0x3fffffe0
	s_lshl_b32 s16, s11, 1
	s_ashr_i32 s11, s10, 31
	v_addc_co_u32_e32 v145, vcc, 0, v133, vcc
	global_load_dwordx4 v[136:139], v[134:135], off
	global_load_dwordx4 v[140:143], v[144:145], off
	v_add_u32_e32 v134, s12, v36
	s_lshl_b64 s[8:9], s[10:11], 15
	v_lshl_or_b32 v144, v134, 2, v37
	s_add_u32 s8, s68, s8
	v_ashrrev_i32_e32 v145, 31, v144
	v_add_co_u32_e32 v132, vcc, s4, v132
	s_addc_u32 s9, s69, s9
	v_lshlrev_b64 v[148:149], 19, v[144:145]
	v_addc_co_u32_e32 v133, vcc, 0, v133, vcc
	v_lshl_add_u64 v[134:135], s[8:9], 0, v[26:27]
	v_lshl_add_u64 v[148:149], s[70:71], 0, v[148:149]
	v_add_co_u32_e32 v144, vcc, s7, v134
	v_lshl_add_u64 v[148:149], v[148:149], 0, s[16:17]
	s_nop 0
	v_addc_co_u32_e32 v145, vcc, 0, v135, vcc
	v_lshl_add_u64 v[148:149], v[148:149], 0, v[24:25]
	global_load_dwordx4 v[144:147], v[144:145], off
	s_add_i32 s18, s18, 4
	global_load_dwordx4 v[148:151], v[148:149], off
	s_addk_i32 s5, 0x80
	s_add_u32 s20, s20, 0x20000
	s_addc_u32 s21, s21, 0
	s_add_u32 s22, s22, 0x20000
	s_addc_u32 s23, s23, 0
	s_cmp_lt_u32 s18, s3
	s_waitcnt vmcnt(19)
	v_lshlrev_b32_e32 v60, 16, v12
	v_lshlrev_b32_e32 v61, 16, v14
	s_waitcnt vmcnt(18)
	v_lshlrev_b32_e32 v68, 16, v9
	v_and_b32_e32 v70, 0xffff0000, v9
	v_lshlrev_b32_e32 v64, 16, v8
	v_and_b32_e32 v66, 0xffff0000, v8
	v_lshlrev_b32_e32 v65, 16, v10
	v_and_b32_e32 v67, 0xffff0000, v10
	v_lshlrev_b32_e32 v69, 16, v11
	v_and_b32_e32 v71, 0xffff0000, v11
	v_and_b32_e32 v12, 0xffff0000, v12
	v_and_b32_e32 v14, 0xffff0000, v14
	v_lshlrev_b32_e32 v62, 16, v13
	v_lshlrev_b32_e32 v63, 16, v15
	v_and_b32_e32 v13, 0xffff0000, v13
	v_and_b32_e32 v15, 0xffff0000, v15
	s_waitcnt vmcnt(17)
	v_and_b32_e32 v9, 0xffff0000, v20
	v_lshlrev_b32_e32 v8, 16, v20
	v_mul_f32_e32 v72, v9, v9
	v_lshlrev_b32_e32 v10, 16, v21
	v_fmac_f32_e32 v72, v8, v8
	v_and_b32_e32 v11, 0xffff0000, v21
	s_waitcnt vmcnt(16)
	v_lshlrev_b32_e32 v73, 16, v16
	v_and_b32_e32 v16, 0xffff0000, v16
	v_mul_f32_e32 v77, v16, v16
	v_fmac_f32_e32 v72, v10, v10
	v_lshlrev_b32_e32 v20, 16, v22
	v_lshlrev_b32_e32 v74, 16, v17
	v_fmac_f32_e32 v77, v73, v73
	v_fmac_f32_e32 v72, v11, v11
	v_and_b32_e32 v21, 0xffff0000, v22
	v_and_b32_e32 v17, 0xffff0000, v17
	v_fmac_f32_e32 v77, v74, v74
	v_fmac_f32_e32 v72, v20, v20
	s_waitcnt vmcnt(15)
	v_lshlrev_b32_e32 v78, 16, v44
	v_and_b32_e32 v44, 0xffff0000, v44
	v_lshlrev_b32_e32 v22, 16, v23
	v_lshlrev_b32_e32 v75, 16, v18
	v_fmac_f32_e32 v77, v17, v17
	v_mul_f32_e32 v86, v44, v44
	v_fmac_f32_e32 v72, v21, v21
	v_and_b32_e32 v23, 0xffff0000, v23
	v_and_b32_e32 v18, 0xffff0000, v18
	v_lshlrev_b32_e32 v79, 16, v45
	v_fmac_f32_e32 v77, v75, v75
	v_fmac_f32_e32 v86, v78, v78
	v_fmac_f32_e32 v72, v22, v22
	v_lshlrev_b32_e32 v76, 16, v19
	v_and_b32_e32 v45, 0xffff0000, v45
	v_fmac_f32_e32 v77, v18, v18
	v_fmac_f32_e32 v86, v79, v79
	v_fmac_f32_e32 v72, v23, v23
	v_and_b32_e32 v19, 0xffff0000, v19
	v_lshlrev_b32_e32 v80, 16, v46
	v_fmac_f32_e32 v77, v76, v76
	v_fmac_f32_e32 v86, v45, v45
	ds_bpermute_b32 v91, v38, v72
	v_and_b32_e32 v46, 0xffff0000, v46
	v_fmac_f32_e32 v77, v19, v19
	v_fmac_f32_e32 v86, v80, v80
	v_lshlrev_b32_e32 v81, 16, v47
	ds_bpermute_b32 v92, v38, v77
	v_fmac_f32_e32 v86, v46, v46
	v_and_b32_e32 v47, 0xffff0000, v47
	v_fmac_f32_e32 v86, v81, v81
	s_waitcnt vmcnt(12)
	v_lshlrev_b32_e32 v93, 16, v56
	v_and_b32_e32 v56, 0xffff0000, v56
	v_fmac_f32_e32 v86, v47, v47
	v_mul_f32_e32 v97, v56, v56
	ds_bpermute_b32 v98, v38, v86
	s_waitcnt lgkmcnt(2)
	v_add_f32_e32 v72, v72, v91
	v_lshlrev_b32_e32 v94, 16, v57
	v_fmac_f32_e32 v97, v93, v93
	ds_bpermute_b32 v91, v39, v72
	v_and_b32_e32 v57, 0xffff0000, v57
	v_fmac_f32_e32 v97, v94, v94
	s_waitcnt lgkmcnt(2)
	v_add_f32_e32 v77, v77, v92
	v_lshlrev_b32_e32 v95, 16, v58
	v_fmac_f32_e32 v97, v57, v57
	ds_bpermute_b32 v92, v39, v77
	v_and_b32_e32 v58, 0xffff0000, v58
	v_fmac_f32_e32 v97, v95, v95
	v_lshlrev_b32_e32 v96, 16, v59
	v_fmac_f32_e32 v97, v58, v58
	s_waitcnt lgkmcnt(2)
	v_add_f32_e32 v86, v86, v98
	v_and_b32_e32 v59, 0xffff0000, v59
	v_fmac_f32_e32 v97, v96, v96
	ds_bpermute_b32 v98, v39, v86
	s_waitcnt lgkmcnt(2)
	v_add_f32_e32 v72, v72, v91
	v_fmac_f32_e32 v97, v59, v59
	ds_bpermute_b32 v99, v40, v72
	ds_bpermute_b32 v91, v38, v97
	s_waitcnt lgkmcnt(3)
	v_add_f32_e32 v77, v77, v92
	ds_bpermute_b32 v92, v40, v77
	s_waitcnt lgkmcnt(3)
	v_add_f32_e32 v86, v86, v98
	ds_bpermute_b32 v98, v40, v86
	s_waitcnt lgkmcnt(3)
	v_add_f32_e32 v72, v72, v99
	s_waitcnt lgkmcnt(2)
	v_add_f32_e32 v91, v97, v91
	ds_bpermute_b32 v99, v41, v72
	ds_bpermute_b32 v97, v39, v91
	s_waitcnt lgkmcnt(3)
	v_add_f32_e32 v77, v77, v92
	ds_bpermute_b32 v92, v41, v77
	s_waitcnt lgkmcnt(3)
	v_add_f32_e32 v86, v86, v98
	ds_bpermute_b32 v98, v41, v86
	s_waitcnt lgkmcnt(3)
	v_add_f32_e32 v72, v72, v99
	s_waitcnt lgkmcnt(2)
	v_add_f32_e32 v91, v91, v97
	v_fmamk_f32 v72, v72, 0x3c000000, v42
	ds_bpermute_b32 v97, v40, v91
	s_waitcnt lgkmcnt(2)
	v_add_f32_e32 v77, v77, v92
	v_mul_f32_e32 v92, 0x4f800000, v72
	v_cmp_gt_f32_e32 vcc, s19, v72
	v_fmamk_f32 v77, v77, 0x3c000000, v42
	v_cmp_gt_f32_e64 s[8:9], s19, v77
	v_cndmask_b32_e32 v72, v72, v92, vcc
	v_mul_f32_e32 v92, 0x4f800000, v77
	v_sqrt_f32_e32 v99, v72
	v_cndmask_b32_e64 v77, v77, v92, s[8:9]
	s_waitcnt lgkmcnt(1)
	v_add_f32_e32 v86, v86, v98
	v_sqrt_f32_e32 v92, v77
	v_fmamk_f32 v86, v86, 0x3c000000, v42
	s_waitcnt lgkmcnt(0)
	v_add_f32_e32 v91, v91, v97
	v_mul_f32_e32 v97, 0x4f800000, v86
	v_cmp_gt_f32_e64 s[10:11], s19, v86
	ds_bpermute_b32 v98, v41, v91
	v_add_u32_e32 v100, 1, v99
	v_cndmask_b32_e64 v86, v86, v97, s[10:11]
	v_add_u32_e32 v97, -1, v99
	v_sqrt_f32_e32 v101, v86
	v_fma_f32 v102, -v97, v99, v72
	v_fma_f32 v103, -v100, v99, v72
	v_add_u32_e32 v104, -1, v92
	v_cmp_ge_f32_e64 s[12:13], 0, v102
	v_add_u32_e32 v105, 1, v92
	v_fma_f32 v102, -v105, v92, v77
	v_cndmask_b32_e64 v97, v99, v97, s[12:13]
	v_fma_f32 v99, -v104, v92, v77
	v_cmp_lt_f32_e64 s[12:13], 0, v103
	s_waitcnt lgkmcnt(0)
	v_add_f32_e32 v91, v91, v98
	v_fmamk_f32 v91, v91, 0x3c000000, v42
	v_cndmask_b32_e64 v97, v97, v100, s[12:13]
	v_cmp_ge_f32_e64 s[12:13], 0, v99
	v_mul_f32_e32 v98, 0x37800000, v97
	v_add_u32_e32 v99, -1, v101
	v_cndmask_b32_e64 v92, v92, v104, s[12:13]
	v_cmp_lt_f32_e64 s[12:13], 0, v102
	v_add_u32_e32 v100, 1, v101
	v_cndmask_b32_e32 v97, v97, v98, vcc
	v_cndmask_b32_e64 v92, v92, v105, s[12:13]
	v_fma_f32 v102, -v99, v101, v86
	v_cmp_class_f32_e64 s[12:13], v72, v43
	v_mul_f32_e32 v98, 0x37800000, v92
	v_fma_f32 v103, -v100, v101, v86
	v_mul_f32_e32 v104, 0x4f800000, v91
	v_cmp_gt_f32_e32 vcc, s19, v91
	v_cndmask_b32_e64 v72, v97, v72, s[12:13]
	v_cmp_ge_f32_e64 s[12:13], 0, v102
	v_cndmask_b32_e64 v92, v92, v98, s[8:9]
	v_cmp_class_f32_e64 s[8:9], v77, v43
	v_cndmask_b32_e64 v97, v101, v99, s[12:13]
	v_cmp_lt_f32_e64 s[12:13], 0, v103
	v_cndmask_b32_e32 v91, v91, v104, vcc
	v_cndmask_b32_e64 v77, v92, v77, s[8:9]
	v_cndmask_b32_e64 v92, v97, v100, s[12:13]
	v_sqrt_f32_e32 v97, v91
	v_div_scale_f32 v98, s[14:15], v72, v72, 1.0
	v_rcp_f32_e32 v100, v98
	v_div_scale_f32 v101, s[8:9], v77, v77, 1.0
	v_mul_f32_e32 v103, 0x37800000, v92
	v_rcp_f32_e32 v104, v101
	v_cndmask_b32_e64 v92, v92, v103, s[10:11]
	v_cmp_class_f32_e64 s[8:9], v86, v43
	v_add_u32_e32 v105, -1, v97
	v_add_u32_e32 v106, 1, v97
	v_cndmask_b32_e64 v86, v92, v86, s[8:9]
	v_div_scale_f32 v92, s[8:9], v86, v86, 1.0
	v_fma_f32 v109, -v105, v97, v91
	v_fma_f32 v107, -v98, v100, 1.0
	v_rcp_f32_e32 v108, v92
	v_fma_f32 v110, -v106, v97, v91
	v_cmp_ge_f32_e64 s[8:9], 0, v109
	v_div_scale_f32 v99, s[14:15], 1.0, v72, 1.0
	v_fmac_f32_e32 v100, v107, v100
	v_fma_f32 v107, -v101, v104, 1.0
	v_cndmask_b32_e64 v97, v97, v105, s[8:9]
	v_cmp_lt_f32_e64 s[8:9], 0, v110
	v_div_scale_f32 v102, s[12:13], 1.0, v77, 1.0
	v_mul_f32_e32 v105, v99, v100
	v_fmac_f32_e32 v104, v107, v104
	v_cndmask_b32_e64 v97, v97, v106, s[8:9]
	v_fma_f32 v106, -v98, v105, v99
	v_mul_f32_e32 v107, v102, v104
	v_mul_f32_e32 v109, 0x37800000, v97
	v_fmac_f32_e32 v105, v106, v100
	v_fma_f32 v106, -v101, v107, v102
	v_fma_f32 v110, -v92, v108, 1.0
	v_cndmask_b32_e32 v97, v97, v109, vcc
	v_cmp_class_f32_e32 vcc, v91, v43
	v_div_scale_f32 v103, s[10:11], 1.0, v86, 1.0
	v_fma_f32 v98, -v98, v105, v99
	v_fmac_f32_e32 v107, v106, v104
	v_fmac_f32_e32 v108, v110, v108
	v_cndmask_b32_e32 v91, v97, v91, vcc
	s_mov_b64 vcc, s[14:15]
	v_div_fmas_f32 v97, v98, v100, v105
	v_fma_f32 v98, -v101, v107, v102
	v_mul_f32_e32 v99, v103, v108
	v_div_scale_f32 v100, s[8:9], v91, v91, 1.0
	s_mov_b64 vcc, s[12:13]
	v_div_fixup_f32 v72, v97, v72, 1.0
	v_div_fmas_f32 v97, v98, v104, v107
	v_fma_f32 v98, -v92, v99, v103
	v_rcp_f32_e32 v102, v100
	v_mul_f32_e32 v8, v72, v8
	v_mul_f32_e32 v20, v72, v20
	v_mul_f32_e32 v9, v72, v9
	v_mul_f32_e32 v21, v72, v21
	v_mul_f32_e32 v10, v72, v10
	v_mul_f32_e32 v22, v72, v22
	v_mul_f32_e32 v11, v72, v11
	v_mul_f32_e32 v23, v72, v23
	v_div_fixup_f32 v72, v97, v77, 1.0
	v_fmac_f32_e32 v99, v98, v108
	v_mul_f32_e32 v8, v0, v8
	v_mul_f32_e32 v20, v4, v20
	v_mul_f32_e32 v9, v1, v9
	v_mul_f32_e32 v21, v5, v21
	v_mul_f32_e32 v10, v2, v10
	v_mul_f32_e32 v22, v6, v22
	v_mul_f32_e32 v11, v3, v11
	v_mul_f32_e32 v23, v7, v23
	v_mul_f32_e32 v73, v72, v73
	v_mul_f32_e32 v75, v72, v75
	v_mul_f32_e32 v16, v72, v16
	v_mul_f32_e32 v18, v72, v18
	v_mul_f32_e32 v74, v72, v74
	v_mul_f32_e32 v76, v72, v76
	v_mul_f32_e32 v17, v72, v17
	v_mul_f32_e32 v19, v72, v19
	v_fma_f32 v72, -v92, v99, v103
	s_mov_b64 vcc, s[10:11]
	v_mul_f32_e32 v8, v8, v60
	v_mul_f32_e32 v20, v20, v61
	v_mul_f32_e32 v9, v9, v12
	v_mul_f32_e32 v12, v21, v14
	v_mul_f32_e32 v10, v10, v62
	v_mul_f32_e32 v14, v22, v63
	v_mul_f32_e32 v11, v11, v13
	v_mul_f32_e32 v13, v23, v15
	v_mul_f32_e32 v15, v0, v73
	v_mul_f32_e32 v21, v4, v75
	v_mul_f32_e32 v16, v1, v16
	v_mul_f32_e32 v18, v5, v18
	v_mul_f32_e32 v22, v2, v74
	v_mul_f32_e32 v23, v6, v76
	v_mul_f32_e32 v17, v3, v17
	v_mul_f32_e32 v19, v7, v19
	v_div_fmas_f32 v60, v72, v108, v99
	v_cvt_pk_bf16_f32 v8, v8, v9
	v_cvt_pk_bf16_f32 v9, v10, v11
	v_cvt_pk_bf16_f32 v10, v20, v12
	v_cvt_pk_bf16_f32 v11, v14, v13
	v_mul_f32_e32 v12, v15, v64
	v_mul_f32_e32 v13, v21, v65
	v_mul_f32_e32 v14, v16, v66
	v_mul_f32_e32 v15, v18, v67
	v_mul_f32_e32 v16, v22, v68
	v_mul_f32_e32 v18, v23, v69
	v_mul_f32_e32 v17, v17, v70
	v_mul_f32_e32 v19, v19, v71
	v_div_fixup_f32 v20, v60, v86, 1.0
	v_fma_f32 v21, -v100, v102, 1.0
	v_div_scale_f32 v101, s[8:9], 1.0, v91, 1.0
	global_store_dwordx4 v[28:29], v[8:11], off
	v_fmac_f32_e32 v102, v21, v102
	v_lshlrev_b32_e32 v82, 16, v48
	v_cvt_pk_bf16_f32 v8, v12, v14
	v_cvt_pk_bf16_f32 v9, v16, v17
	v_cvt_pk_bf16_f32 v10, v13, v15
	v_cvt_pk_bf16_f32 v11, v18, v19
	v_mul_f32_e32 v12, v20, v78
	v_mul_f32_e32 v13, v20, v80
	v_mul_f32_e32 v14, v20, v44
	v_mul_f32_e32 v15, v20, v46
	v_mul_f32_e32 v16, v20, v79
	v_mul_f32_e32 v17, v20, v81
	v_mul_f32_e32 v18, v20, v45
	v_mul_f32_e32 v19, v20, v47
	v_lshlrev_b32_e32 v83, 16, v50
	v_and_b32_e32 v48, 0xffff0000, v48
	v_and_b32_e32 v50, 0xffff0000, v50
	v_lshlrev_b32_e32 v84, 16, v49
	v_lshlrev_b32_e32 v85, 16, v51
	v_and_b32_e32 v49, 0xffff0000, v49
	v_and_b32_e32 v51, 0xffff0000, v51
	global_store_dwordx4 v[30:31], v[8:11], off
	s_mov_b64 vcc, s[8:9]
	v_lshlrev_b32_e32 v87, 16, v52
	v_mul_f32_e32 v8, v0, v12
	v_mul_f32_e32 v9, v4, v13
	v_mul_f32_e32 v10, v1, v14
	v_mul_f32_e32 v11, v5, v15
	v_mul_f32_e32 v12, v2, v16
	v_mul_f32_e32 v13, v6, v17
	v_mul_f32_e32 v14, v3, v18
	v_mul_f32_e32 v15, v7, v19
	v_mul_f32_e32 v16, v101, v102
	v_mul_f32_e32 v8, v8, v82
	v_mul_f32_e32 v17, v9, v83
	v_mul_f32_e32 v9, v10, v48
	v_mul_f32_e32 v10, v11, v50
	v_mul_f32_e32 v11, v12, v84
	v_mul_f32_e32 v12, v13, v85
	v_mul_f32_e32 v13, v14, v49
	v_mul_f32_e32 v14, v15, v51
	v_fma_f32 v15, -v100, v16, v101
	v_cvt_pk_bf16_f32 v8, v8, v9
	v_fmac_f32_e32 v16, v15, v102
	v_cvt_pk_bf16_f32 v9, v11, v13
	v_cvt_pk_bf16_f32 v10, v17, v10
	v_cvt_pk_bf16_f32 v11, v12, v14
	global_store_dwordx4 v[32:33], v[8:11], off
	v_lshlrev_b32_e32 v88, 16, v54
	v_and_b32_e32 v52, 0xffff0000, v52
	v_fma_f32 v8, -v100, v16, v101
	v_div_fmas_f32 v8, v8, v102, v16
	v_div_fixup_f32 v8, v8, v91, 1.0
	v_mul_f32_e32 v9, v8, v93
	v_mul_f32_e32 v10, v8, v95
	v_mul_f32_e32 v11, v8, v56
	v_add_co_u32_e32 v12, vcc, s4, v34
	v_mul_f32_e32 v14, v8, v58
	v_mul_f32_e32 v15, v8, v94
	v_mul_f32_e32 v16, v8, v96
	v_mul_f32_e32 v17, v8, v57
	v_mul_f32_e32 v8, v8, v59
	v_mul_f32_e32 v9, v0, v9
	v_mul_f32_e32 v10, v4, v10
	v_mul_f32_e32 v11, v1, v11
	v_and_b32_e32 v54, 0xffff0000, v54
	v_lshlrev_b32_e32 v89, 16, v53
	v_lshlrev_b32_e32 v90, 16, v55
	v_and_b32_e32 v53, 0xffff0000, v53
	v_and_b32_e32 v55, 0xffff0000, v55
	v_addc_co_u32_e32 v13, vcc, 0, v35, vcc
	v_mul_f32_e32 v14, v5, v14
	v_mul_f32_e32 v15, v2, v15
	v_mul_f32_e32 v16, v6, v16
	v_mul_f32_e32 v17, v3, v17
	v_mul_f32_e32 v8, v7, v8
	v_mul_f32_e32 v9, v9, v87
	v_mul_f32_e32 v10, v10, v88
	v_mul_f32_e32 v11, v11, v52
	v_mul_f32_e32 v14, v14, v54
	v_mul_f32_e32 v15, v15, v89
	v_mul_f32_e32 v16, v16, v90
	v_mul_f32_e32 v17, v17, v53
	v_mul_f32_e32 v18, v8, v55
	v_cvt_pk_bf16_f32 v8, v9, v11
	v_cvt_pk_bf16_f32 v9, v15, v17
	v_cvt_pk_bf16_f32 v10, v10, v14
	v_cvt_pk_bf16_f32 v11, v16, v18
	global_store_dwordx4 v[12:13], v[8:11], off
	s_nop 1
	v_lshl_add_u64 v[12:13], s[22:23], 0, v[26:27]
	v_add_co_u32_e32 v10, vcc, s6, v12
	v_lshl_add_u64 v[8:9], s[20:21], 0, v[26:27]
	s_nop 0
	v_addc_co_u32_e32 v11, vcc, 0, v13, vcc
	v_add_co_u32_e32 v16, vcc, s6, v8
	s_ashr_i32 s9, s18, 8
	s_nop 0
	v_addc_co_u32_e32 v17, vcc, 0, v9, vcc
	v_add_co_u32_e32 v28, vcc, s24, v12
	s_add_i32 s11, s18, 1
	s_and_b32 s12, s9, 0x3fffffe0
	v_addc_co_u32_e32 v29, vcc, 0, v13, vcc
	s_add_i32 s10, s5, 0xffffffa0
	s_sub_i32 s15, s5, 64
	s_add_i32 s8, s18, 2
	s_ashr_i32 s14, s11, 8
	v_add_co_u32_e32 v30, vcc, s24, v8
	v_add_u32_e32 v18, s12, v36
	s_sub_i32 s16, s5, 32
	s_and_b32 s13, s10, 0x3ffe0
	s_and_b32 s10, s15, 0x3ffe0
	s_ashr_i32 s15, s8, 8
	v_addc_co_u32_e32 v31, vcc, 0, v9, vcc
	global_load_dwordx4 v[12:15], v[10:11], off
	s_and_b32 s12, s14, 0x3fffffe0
	global_load_dwordx4 v[8:11], v[16:17], off
	v_lshl_or_b32 v16, v18, 2, v37
	s_and_b32 s11, s16, 0x3ffe0
	s_lshl_b32 s16, s13, 1
	s_and_b32 s13, s15, 0x3fffffe0
	v_add_u32_e32 v18, s12, v36
	v_ashrrev_i32_e32 v17, 31, v16
	v_add_u32_e32 v19, s13, v36
	v_lshl_or_b32 v18, v18, 2, v37
	v_lshlrev_b64 v[16:17], 19, v[16:17]
	v_lshl_or_b32 v20, v19, 2, v37
	v_ashrrev_i32_e32 v19, 31, v18
	v_lshl_add_u64 v[16:17], s[70:71], 0, v[16:17]
	v_ashrrev_i32_e32 v21, 31, v20
	v_lshlrev_b64 v[18:19], 19, v[18:19]
	v_lshl_add_u64 v[16:17], v[16:17], 0, s[16:17]
	v_lshlrev_b64 v[20:21], 19, v[20:21]
	v_lshl_add_u64 v[18:19], s[70:71], 0, v[18:19]
	s_lshl_b32 s16, s10, 1
	v_lshl_add_u64 v[16:17], v[16:17], 0, v[24:25]
	s_ashr_i32 s9, s8, 31
	v_lshl_add_u64 v[32:33], s[70:71], 0, v[20:21]
	v_lshl_add_u64 v[18:19], v[18:19], 0, s[16:17]
	s_lshl_b32 s16, s11, 1
	global_load_dwordx4 v[20:23], v[16:17], off
	s_lshl_b64 s[8:9], s[8:9], 15
	v_lshl_add_u64 v[16:17], v[18:19], 0, v[24:25]
	v_lshl_add_u64 v[18:19], v[32:33], 0, s[16:17]
	s_add_u32 s8, s68, s8
	v_lshl_add_u64 v[34:35], v[18:19], 0, v[24:25]
	global_load_dwordx4 v[16:19], v[16:17], off
	s_addc_u32 s9, s69, s9
	s_add_i32 s10, s18, 3
	v_lshl_add_u64 v[32:33], s[8:9], 0, v[26:27]
	s_ashr_i32 s8, s10, 8
	s_and_b32 s11, s5, 0x3ffe0
	v_add_co_u32_e32 v52, vcc, s7, v32
	s_and_b32 s12, s8, 0x3fffffe0
	s_lshl_b32 s16, s11, 1
	s_ashr_i32 s11, s10, 31
	v_addc_co_u32_e32 v53, vcc, 0, v33, vcc
	global_load_dwordx4 v[44:47], v[34:35], off
	global_load_dwordx4 v[48:51], v[52:53], off
	v_add_u32_e32 v34, s12, v36
	s_lshl_b64 s[8:9], s[10:11], 15
	v_lshl_or_b32 v52, v34, 2, v37
	s_add_u32 s8, s68, s8
	v_ashrrev_i32_e32 v53, 31, v52
	v_add_co_u32_e32 v32, vcc, s4, v32
	s_addc_u32 s9, s69, s9
	v_lshlrev_b64 v[56:57], 19, v[52:53]
	v_addc_co_u32_e32 v33, vcc, 0, v33, vcc
	v_lshl_add_u64 v[34:35], s[8:9], 0, v[26:27]
	v_lshl_add_u64 v[56:57], s[70:71], 0, v[56:57]
	v_add_co_u32_e32 v52, vcc, s7, v34
	v_lshl_add_u64 v[56:57], v[56:57], 0, s[16:17]
	s_nop 0
	v_addc_co_u32_e32 v53, vcc, 0, v35, vcc
	v_lshl_add_u64 v[56:57], v[56:57], 0, v[24:25]
	global_load_dwordx4 v[52:55], v[52:53], off
	s_add_i32 s18, s18, 4
	global_load_dwordx4 v[56:59], v[56:57], off
	s_addk_i32 s5, 0x80
	s_add_u32 s20, s20, 0x20000
	s_addc_u32 s21, s21, 0
	s_add_u32 s22, s22, 0x20000
	s_addc_u32 s23, s23, 0
	s_cmp_lt_u32 s18, s3
	s_sub_u32 s98, s98, 1
	s_cmp_lg_u32 s98, 0
	s_cbranch_scc1 .Lhn_loop
	s_waitcnt vmcnt(19)
	v_lshlrev_b32_e32 v152, 16, v116
	v_lshlrev_b32_e32 v153, 16, v118
	s_waitcnt vmcnt(18)
	v_lshlrev_b32_e32 v160, 16, v113
	v_and_b32_e32 v162, 0xffff0000, v113
	v_lshlrev_b32_e32 v156, 16, v112
	v_and_b32_e32 v158, 0xffff0000, v112
	v_lshlrev_b32_e32 v157, 16, v114
	v_and_b32_e32 v159, 0xffff0000, v114
	v_lshlrev_b32_e32 v161, 16, v115
	v_and_b32_e32 v163, 0xffff0000, v115
	v_and_b32_e32 v116, 0xffff0000, v116
	v_and_b32_e32 v118, 0xffff0000, v118
	v_lshlrev_b32_e32 v154, 16, v117
	v_lshlrev_b32_e32 v155, 16, v119
	v_and_b32_e32 v117, 0xffff0000, v117
	v_and_b32_e32 v119, 0xffff0000, v119
	s_waitcnt vmcnt(17)
	v_and_b32_e32 v113, 0xffff0000, v124
	v_lshlrev_b32_e32 v112, 16, v124
	v_mul_f32_e32 v164, v113, v113
	v_lshlrev_b32_e32 v114, 16, v125
	v_fmac_f32_e32 v164, v112, v112
	v_and_b32_e32 v115, 0xffff0000, v125
	s_waitcnt vmcnt(16)
	v_lshlrev_b32_e32 v165, 16, v120
	v_and_b32_e32 v120, 0xffff0000, v120
	v_mul_f32_e32 v169, v120, v120
	v_fmac_f32_e32 v164, v114, v114
	v_lshlrev_b32_e32 v124, 16, v126
	v_lshlrev_b32_e32 v166, 16, v121
	v_fmac_f32_e32 v169, v165, v165
	v_fmac_f32_e32 v164, v115, v115
	v_and_b32_e32 v125, 0xffff0000, v126
	v_and_b32_e32 v121, 0xffff0000, v121
	v_fmac_f32_e32 v169, v166, v166
	v_fmac_f32_e32 v164, v124, v124
	s_waitcnt vmcnt(15)
	v_lshlrev_b32_e32 v170, 16, v136
	v_and_b32_e32 v136, 0xffff0000, v136
	v_lshlrev_b32_e32 v126, 16, v127
	v_lshlrev_b32_e32 v167, 16, v122
	v_fmac_f32_e32 v169, v121, v121
	v_mul_f32_e32 v192, v136, v136
	v_fmac_f32_e32 v164, v125, v125
	v_and_b32_e32 v127, 0xffff0000, v127
	v_and_b32_e32 v122, 0xffff0000, v122
	v_lshlrev_b32_e32 v171, 16, v137
	v_fmac_f32_e32 v169, v167, v167
	v_fmac_f32_e32 v192, v170, v170
	v_fmac_f32_e32 v164, v126, v126
	v_lshlrev_b32_e32 v168, 16, v123
	v_and_b32_e32 v137, 0xffff0000, v137
	v_fmac_f32_e32 v169, v122, v122
	v_fmac_f32_e32 v192, v171, v171
	v_fmac_f32_e32 v164, v127, v127
	v_and_b32_e32 v123, 0xffff0000, v123
	v_lshlrev_b32_e32 v186, 16, v138
	v_fmac_f32_e32 v169, v168, v168
	v_fmac_f32_e32 v192, v137, v137
	ds_bpermute_b32 v197, v38, v164
	v_and_b32_e32 v138, 0xffff0000, v138
	v_fmac_f32_e32 v169, v123, v123
	v_fmac_f32_e32 v192, v186, v186
	v_lshlrev_b32_e32 v187, 16, v139
	ds_bpermute_b32 v198, v38, v169
	v_fmac_f32_e32 v192, v138, v138
	v_and_b32_e32 v139, 0xffff0000, v139
	v_fmac_f32_e32 v192, v187, v187
	s_waitcnt vmcnt(12)
	v_lshlrev_b32_e32 v199, 16, v148
	v_and_b32_e32 v148, 0xffff0000, v148
	v_fmac_f32_e32 v192, v139, v139
	v_mul_f32_e32 v203, v148, v148
	ds_bpermute_b32 v204, v38, v192
	s_waitcnt lgkmcnt(2)
	v_add_f32_e32 v164, v164, v197
	v_lshlrev_b32_e32 v200, 16, v149
	v_fmac_f32_e32 v203, v199, v199
	ds_bpermute_b32 v197, v39, v164
	v_and_b32_e32 v149, 0xffff0000, v149
	v_fmac_f32_e32 v203, v200, v200
	s_waitcnt lgkmcnt(2)
	v_add_f32_e32 v169, v169, v198
	v_lshlrev_b32_e32 v201, 16, v150
	v_fmac_f32_e32 v203, v149, v149
	ds_bpermute_b32 v198, v39, v169
	v_and_b32_e32 v150, 0xffff0000, v150
	v_fmac_f32_e32 v203, v201, v201
	v_lshlrev_b32_e32 v202, 16, v151
	v_fmac_f32_e32 v203, v150, v150
	s_waitcnt lgkmcnt(2)
	v_add_f32_e32 v192, v192, v204
	v_and_b32_e32 v151, 0xffff0000, v151
	v_fmac_f32_e32 v203, v202, v202
	ds_bpermute_b32 v204, v39, v192
	s_waitcnt lgkmcnt(2)
	v_add_f32_e32 v164, v164, v197
	v_fmac_f32_e32 v203, v151, v151
	ds_bpermute_b32 v205, v40, v164
	ds_bpermute_b32 v197, v38, v203
	s_waitcnt lgkmcnt(3)
	v_add_f32_e32 v169, v169, v198
	ds_bpermute_b32 v198, v40, v169
	s_waitcnt lgkmcnt(3)
	v_add_f32_e32 v192, v192, v204
	ds_bpermute_b32 v204, v40, v192
	s_waitcnt lgkmcnt(3)
	v_add_f32_e32 v164, v164, v205
	s_waitcnt lgkmcnt(2)
	v_add_f32_e32 v197, v203, v197
	ds_bpermute_b32 v205, v41, v164
	ds_bpermute_b32 v203, v39, v197
	s_waitcnt lgkmcnt(3)
	v_add_f32_e32 v169, v169, v198
	ds_bpermute_b32 v198, v41, v169
	s_waitcnt lgkmcnt(3)
	v_add_f32_e32 v192, v192, v204
	ds_bpermute_b32 v204, v41, v192
	s_waitcnt lgkmcnt(3)
	v_add_f32_e32 v164, v164, v205
	s_waitcnt lgkmcnt(2)
	v_add_f32_e32 v197, v197, v203
	v_fmamk_f32 v164, v164, 0x3c000000, v42
	ds_bpermute_b32 v203, v40, v197
	s_waitcnt lgkmcnt(2)
	v_add_f32_e32 v169, v169, v198
	v_mul_f32_e32 v198, 0x4f800000, v164
	v_cmp_gt_f32_e32 vcc, s19, v164
	v_fmamk_f32 v169, v169, 0x3c000000, v42
	v_cmp_gt_f32_e64 s[8:9], s19, v169
	v_cndmask_b32_e32 v164, v164, v198, vcc
	v_mul_f32_e32 v198, 0x4f800000, v169
	v_sqrt_f32_e32 v205, v164
	v_cndmask_b32_e64 v169, v169, v198, s[8:9]
	s_waitcnt lgkmcnt(1)
	v_add_f32_e32 v192, v192, v204
	v_sqrt_f32_e32 v198, v169
	v_fmamk_f32 v192, v192, 0x3c000000, v42
	s_waitcnt lgkmcnt(0)
	v_add_f32_e32 v197, v197, v203
	v_mul_f32_e32 v203, 0x4f800000, v192
	v_cmp_gt_f32_e64 s[10:11], s19, v192
	ds_bpermute_b32 v204, v41, v197
	v_add_u32_e32 v206, 1, v205
	v_cndmask_b32_e64 v192, v192, v203, s[10:11]
	v_add_u32_e32 v203, -1, v205
	v_sqrt_f32_e32 v207, v192
	v_fma_f32 v208, -v203, v205, v164
	v_fma_f32 v209, -v206, v205, v164
	v_add_u32_e32 v210, -1, v198
	v_cmp_ge_f32_e64 s[12:13], 0, v208
	v_add_u32_e32 v211, 1, v198
	v_fma_f32 v208, -v211, v198, v169
	v_cndmask_b32_e64 v203, v205, v203, s[12:13]
	v_fma_f32 v205, -v210, v198, v169
	v_cmp_lt_f32_e64 s[12:13], 0, v209
	s_waitcnt lgkmcnt(0)
	v_add_f32_e32 v197, v197, v204
	v_fmamk_f32 v197, v197, 0x3c000000, v42
	v_cndmask_b32_e64 v203, v203, v206, s[12:13]
	v_cmp_ge_f32_e64 s[12:13], 0, v205
	v_mul_f32_e32 v204, 0x37800000, v203
	v_add_u32_e32 v205, -1, v207
	v_cndmask_b32_e64 v198, v198, v210, s[12:13]
	v_cmp_lt_f32_e64 s[12:13], 0, v208
	v_add_u32_e32 v206, 1, v207
	v_cndmask_b32_e32 v203, v203, v204, vcc
	v_cndmask_b32_e64 v198, v198, v211, s[12:13]
	v_fma_f32 v208, -v205, v207, v192
	v_cmp_class_f32_e64 s[12:13], v164, v43
	v_mul_f32_e32 v204, 0x37800000, v198
	v_fma_f32 v209, -v206, v207, v192
	v_mul_f32_e32 v210, 0x4f800000, v197
	v_cmp_gt_f32_e32 vcc, s19, v197
	v_cndmask_b32_e64 v164, v203, v164, s[12:13]
	v_cmp_ge_f32_e64 s[12:13], 0, v208
	v_cndmask_b32_e64 v198, v198, v204, s[8:9]
	v_cmp_class_f32_e64 s[8:9], v169, v43
	v_cndmask_b32_e64 v203, v207, v205, s[12:13]
	v_cmp_lt_f32_e64 s[12:13], 0, v209
	v_cndmask_b32_e32 v197, v197, v210, vcc
	v_cndmask_b32_e64 v169, v198, v169, s[8:9]
	v_cndmask_b32_e64 v198, v203, v206, s[12:13]
	v_sqrt_f32_e32 v203, v197
	v_div_scale_f32 v204, s[14:15], v164, v164, 1.0
	v_rcp_f32_e32 v206, v204
	v_div_scale_f32 v207, s[8:9], v169, v169, 1.0
	v_mul_f32_e32 v209, 0x37800000, v198
	v_rcp_f32_e32 v210, v207
	v_cndmask_b32_e64 v198, v198, v209, s[10:11]
	v_cmp_class_f32_e64 s[8:9], v192, v43
	v_add_u32_e32 v211, -1, v203
	v_add_u32_e32 v212, 1, v203
	v_cndmask_b32_e64 v192, v198, v192, s[8:9]
	v_div_scale_f32 v198, s[8:9], v192, v192, 1.0
	v_fma_f32 v215, -v211, v203, v197
	v_fma_f32 v213, -v204, v206, 1.0
	v_rcp_f32_e32 v214, v198
	v_fma_f32 v216, -v212, v203, v197
	v_cmp_ge_f32_e64 s[8:9], 0, v215
	v_div_scale_f32 v205, s[14:15], 1.0, v164, 1.0
	v_fmac_f32_e32 v206, v213, v206
	v_fma_f32 v213, -v207, v210, 1.0
	v_cndmask_b32_e64 v203, v203, v211, s[8:9]
	v_cmp_lt_f32_e64 s[8:9], 0, v216
	v_div_scale_f32 v208, s[12:13], 1.0, v169, 1.0
	v_mul_f32_e32 v211, v205, v206
	v_fmac_f32_e32 v210, v213, v210
	v_cndmask_b32_e64 v203, v203, v212, s[8:9]
	v_fma_f32 v212, -v204, v211, v205
	v_mul_f32_e32 v213, v208, v210
	v_mul_f32_e32 v215, 0x37800000, v203
	v_fmac_f32_e32 v211, v212, v206
	v_fma_f32 v212, -v207, v213, v208
	v_fma_f32 v216, -v198, v214, 1.0
	v_cndmask_b32_e32 v203, v203, v215, vcc
	v_cmp_class_f32_e32 vcc, v197, v43
	v_div_scale_f32 v209, s[10:11], 1.0, v192, 1.0
	v_fma_f32 v204, -v204, v211, v205
	v_fmac_f32_e32 v213, v212, v210
	v_fmac_f32_e32 v214, v216, v214
	v_cndmask_b32_e32 v197, v203, v197, vcc
	s_mov_b64 vcc, s[14:15]
	v_div_fmas_f32 v203, v204, v206, v211
	v_fma_f32 v204, -v207, v213, v208
	v_mul_f32_e32 v205, v209, v214
	v_div_scale_f32 v206, s[8:9], v197, v197, 1.0
	s_mov_b64 vcc, s[12:13]
	v_div_fixup_f32 v164, v203, v164, 1.0
	v_div_fmas_f32 v203, v204, v210, v213
	v_fma_f32 v204, -v198, v205, v209
	v_rcp_f32_e32 v208, v206
	v_mul_f32_e32 v112, v164, v112
	v_mul_f32_e32 v124, v164, v124
	v_mul_f32_e32 v113, v164, v113
	v_mul_f32_e32 v125, v164, v125
	v_mul_f32_e32 v114, v164, v114
	v_mul_f32_e32 v126, v164, v126
	v_mul_f32_e32 v115, v164, v115
	v_mul_f32_e32 v127, v164, v127
	v_div_fixup_f32 v164, v203, v169, 1.0
	v_fmac_f32_e32 v205, v204, v214
	v_mul_f32_e32 v112, v0, v112
	v_mul_f32_e32 v124, v4, v124
	v_mul_f32_e32 v113, v1, v113
	v_mul_f32_e32 v125, v5, v125
	v_mul_f32_e32 v114, v2, v114
	v_mul_f32_e32 v126, v6, v126
	v_mul_f32_e32 v115, v3, v115
	v_mul_f32_e32 v127, v7, v127
	v_mul_f32_e32 v165, v164, v165
	v_mul_f32_e32 v167, v164, v167
	v_mul_f32_e32 v120, v164, v120
	v_mul_f32_e32 v122, v164, v122
	v_mul_f32_e32 v166, v164, v166
	v_mul_f32_e32 v168, v164, v168
	v_mul_f32_e32 v121, v164, v121
	v_mul_f32_e32 v123, v164, v123
	v_fma_f32 v164, -v198, v205, v209
	s_mov_b64 vcc, s[10:11]
	v_mul_f32_e32 v112, v112, v152
	v_mul_f32_e32 v124, v124, v153
	v_mul_f32_e32 v113, v113, v116
	v_mul_f32_e32 v116, v125, v118
	v_mul_f32_e32 v114, v114, v154
	v_mul_f32_e32 v118, v126, v155
	v_mul_f32_e32 v115, v115, v117
	v_mul_f32_e32 v117, v127, v119
	v_mul_f32_e32 v119, v0, v165
	v_mul_f32_e32 v125, v4, v167
	v_mul_f32_e32 v120, v1, v120
	v_mul_f32_e32 v122, v5, v122
	v_mul_f32_e32 v126, v2, v166
	v_mul_f32_e32 v127, v6, v168
	v_mul_f32_e32 v121, v3, v121
	v_mul_f32_e32 v123, v7, v123
	v_div_fmas_f32 v152, v164, v214, v205
	v_cvt_pk_bf16_f32 v112, v112, v113
	v_cvt_pk_bf16_f32 v113, v114, v115
	v_cvt_pk_bf16_f32 v114, v124, v116
	v_cvt_pk_bf16_f32 v115, v118, v117
	v_mul_f32_e32 v116, v119, v156
	v_mul_f32_e32 v117, v125, v157
	v_mul_f32_e32 v118, v120, v158
	v_mul_f32_e32 v119, v122, v159
	v_mul_f32_e32 v120, v126, v160
	v_mul_f32_e32 v122, v127, v161
	v_mul_f32_e32 v121, v121, v162
	v_mul_f32_e32 v123, v123, v163
	v_div_fixup_f32 v124, v152, v192, 1.0
	v_fma_f32 v125, -v206, v208, 1.0
	v_div_scale_f32 v207, s[8:9], 1.0, v197, 1.0
	global_store_dwordx4 v[128:129], v[112:115], off
	v_fmac_f32_e32 v208, v125, v208
	v_lshlrev_b32_e32 v188, 16, v140
	v_cvt_pk_bf16_f32 v112, v116, v118
	v_cvt_pk_bf16_f32 v113, v120, v121
	v_cvt_pk_bf16_f32 v114, v117, v119
	v_cvt_pk_bf16_f32 v115, v122, v123
	v_mul_f32_e32 v116, v124, v170
	v_mul_f32_e32 v117, v124, v186
	v_mul_f32_e32 v118, v124, v136
	v_mul_f32_e32 v119, v124, v138
	v_mul_f32_e32 v120, v124, v171
	v_mul_f32_e32 v121, v124, v187
	v_mul_f32_e32 v122, v124, v137
	v_mul_f32_e32 v123, v124, v139
	v_lshlrev_b32_e32 v189, 16, v142
	v_and_b32_e32 v140, 0xffff0000, v140
	v_and_b32_e32 v142, 0xffff0000, v142
	v_lshlrev_b32_e32 v190, 16, v141
	v_lshlrev_b32_e32 v191, 16, v143
	v_and_b32_e32 v141, 0xffff0000, v141
	v_and_b32_e32 v143, 0xffff0000, v143
	global_store_dwordx4 v[130:131], v[112:115], off
	s_mov_b64 vcc, s[8:9]
	v_lshlrev_b32_e32 v193, 16, v144
	v_mul_f32_e32 v112, v0, v116
	v_mul_f32_e32 v113, v4, v117
	v_mul_f32_e32 v114, v1, v118
	v_mul_f32_e32 v115, v5, v119
	v_mul_f32_e32 v116, v2, v120
	v_mul_f32_e32 v117, v6, v121
	v_mul_f32_e32 v118, v3, v122
	v_mul_f32_e32 v119, v7, v123
	v_mul_f32_e32 v120, v207, v208
	v_mul_f32_e32 v112, v112, v188
	v_mul_f32_e32 v121, v113, v189
	v_mul_f32_e32 v113, v114, v140
	v_mul_f32_e32 v114, v115, v142
	v_mul_f32_e32 v115, v116, v190
	v_mul_f32_e32 v116, v117, v191
	v_mul_f32_e32 v117, v118, v141
	v_mul_f32_e32 v118, v119, v143
	v_fma_f32 v119, -v206, v120, v207
	v_cvt_pk_bf16_f32 v112, v112, v113
	v_fmac_f32_e32 v120, v119, v208
	v_cvt_pk_bf16_f32 v113, v115, v117
	v_cvt_pk_bf16_f32 v114, v121, v114
	v_cvt_pk_bf16_f32 v115, v116, v118
	global_store_dwordx4 v[132:133], v[112:115], off
	v_lshlrev_b32_e32 v194, 16, v146
	v_and_b32_e32 v144, 0xffff0000, v144
	v_fma_f32 v112, -v206, v120, v207
	v_div_fmas_f32 v112, v112, v208, v120
	v_div_fixup_f32 v112, v112, v197, 1.0
	v_mul_f32_e32 v113, v112, v199
	v_mul_f32_e32 v114, v112, v201
	v_mul_f32_e32 v115, v112, v148
	v_add_co_u32_e32 v116, vcc, s4, v134
	v_mul_f32_e32 v118, v112, v150
	v_mul_f32_e32 v119, v112, v200
	v_mul_f32_e32 v120, v112, v202
	v_mul_f32_e32 v121, v112, v149
	v_mul_f32_e32 v112, v112, v151
	v_mul_f32_e32 v113, v0, v113
	v_mul_f32_e32 v114, v4, v114
	v_mul_f32_e32 v115, v1, v115
	v_and_b32_e32 v146, 0xffff0000, v146
	v_lshlrev_b32_e32 v195, 16, v145
	v_lshlrev_b32_e32 v196, 16, v147
	v_and_b32_e32 v145, 0xffff0000, v145
	v_and_b32_e32 v147, 0xffff0000, v147
	v_addc_co_u32_e32 v117, vcc, 0, v135, vcc
	v_mul_f32_e32 v118, v5, v118
	v_mul_f32_e32 v119, v2, v119
	v_mul_f32_e32 v120, v6, v120
	v_mul_f32_e32 v121, v3, v121
	v_mul_f32_e32 v112, v7, v112
	v_mul_f32_e32 v113, v113, v193
	v_mul_f32_e32 v114, v114, v194
	v_mul_f32_e32 v115, v115, v144
	v_mul_f32_e32 v118, v118, v146
	v_mul_f32_e32 v119, v119, v195
	v_mul_f32_e32 v120, v120, v196
	v_mul_f32_e32 v121, v121, v145
	v_mul_f32_e32 v122, v112, v147
	v_cvt_pk_bf16_f32 v112, v113, v115
	v_cvt_pk_bf16_f32 v113, v119, v121
	v_cvt_pk_bf16_f32 v114, v114, v118
	v_cvt_pk_bf16_f32 v115, v120, v122
	global_store_dwordx4 v[116:117], v[112:115], off
	s_nop 1
	v_lshl_add_u64 v[116:117], s[22:23], 0, v[26:27]
	v_add_co_u32_e32 v114, vcc, s6, v116
	v_lshl_add_u64 v[112:113], s[20:21], 0, v[26:27]
	s_nop 0
	v_addc_co_u32_e32 v115, vcc, 0, v117, vcc
	v_add_co_u32_e32 v120, vcc, s6, v112
	s_ashr_i32 s9, s18, 8
	s_nop 0
	v_addc_co_u32_e32 v121, vcc, 0, v113, vcc
	v_add_co_u32_e32 v128, vcc, s24, v116
	s_add_i32 s11, s18, 1
	s_and_b32 s12, s9, 0x3fffffe0
	v_addc_co_u32_e32 v129, vcc, 0, v117, vcc
	s_add_i32 s10, s5, 0xffffffa0
	s_sub_i32 s15, s5, 64
	s_add_i32 s8, s18, 2
	s_ashr_i32 s14, s11, 8
	v_add_co_u32_e32 v130, vcc, s24, v112
	v_add_u32_e32 v122, s12, v36
	s_sub_i32 s16, s5, 32
	s_and_b32 s13, s10, 0x3ffe0
	s_and_b32 s10, s15, 0x3ffe0
	s_ashr_i32 s15, s8, 8
	v_addc_co_u32_e32 v131, vcc, 0, v113, vcc
	global_load_dwordx4 v[116:119], v[114:115], off
	s_and_b32 s12, s14, 0x3fffffe0
	global_load_dwordx4 v[112:115], v[120:121], off
	v_lshl_or_b32 v120, v122, 2, v37
	s_and_b32 s11, s16, 0x3ffe0
	s_lshl_b32 s16, s13, 1
	s_and_b32 s13, s15, 0x3fffffe0
	v_add_u32_e32 v122, s12, v36
	v_ashrrev_i32_e32 v121, 31, v120
	v_add_u32_e32 v123, s13, v36
	v_lshl_or_b32 v122, v122, 2, v37
	v_lshlrev_b64 v[120:121], 19, v[120:121]
	v_lshl_or_b32 v124, v123, 2, v37
	v_ashrrev_i32_e32 v123, 31, v122
	v_lshl_add_u64 v[120:121], s[70:71], 0, v[120:121]
	v_ashrrev_i32_e32 v125, 31, v124
	v_lshlrev_b64 v[122:123], 19, v[122:123]
	v_lshl_add_u64 v[120:121], v[120:121], 0, s[16:17]
	v_lshlrev_b64 v[124:125], 19, v[124:125]
	v_lshl_add_u64 v[122:123], s[70:71], 0, v[122:123]
	s_lshl_b32 s16, s10, 1
	v_lshl_add_u64 v[120:121], v[120:121], 0, v[24:25]
	s_ashr_i32 s9, s8, 31
	v_lshl_add_u64 v[132:133], s[70:71], 0, v[124:125]
	v_lshl_add_u64 v[122:123], v[122:123], 0, s[16:17]
	s_lshl_b32 s16, s11, 1
	global_load_dwordx4 v[124:127], v[120:121], off
	s_lshl_b64 s[8:9], s[8:9], 15
	v_lshl_add_u64 v[120:121], v[122:123], 0, v[24:25]
	v_lshl_add_u64 v[122:123], v[132:133], 0, s[16:17]
	s_add_u32 s8, s68, s8
	v_lshl_add_u64 v[134:135], v[122:123], 0, v[24:25]
	global_load_dwordx4 v[120:123], v[120:121], off
	s_addc_u32 s9, s69, s9
	s_add_i32 s10, s18, 3
	v_lshl_add_u64 v[132:133], s[8:9], 0, v[26:27]
	s_ashr_i32 s8, s10, 8
	s_and_b32 s11, s5, 0x3ffe0
	v_add_co_u32_e32 v144, vcc, s7, v132
	s_and_b32 s12, s8, 0x3fffffe0
	s_lshl_b32 s16, s11, 1
	s_ashr_i32 s11, s10, 31
	v_addc_co_u32_e32 v145, vcc, 0, v133, vcc
	global_load_dwordx4 v[136:139], v[134:135], off
	global_load_dwordx4 v[140:143], v[144:145], off
	v_add_u32_e32 v134, s12, v36
	s_lshl_b64 s[8:9], s[10:11], 15
	v_lshl_or_b32 v144, v134, 2, v37
	s_add_u32 s8, s68, s8
	v_ashrrev_i32_e32 v145, 31, v144
	v_add_co_u32_e32 v132, vcc, s4, v132
	s_addc_u32 s9, s69, s9
	v_lshlrev_b64 v[148:149], 19, v[144:145]
	v_addc_co_u32_e32 v133, vcc, 0, v133, vcc
	v_lshl_add_u64 v[134:135], s[8:9], 0, v[26:27]
	v_lshl_add_u64 v[148:149], s[70:71], 0, v[148:149]
	v_add_co_u32_e32 v144, vcc, s7, v134
	v_lshl_add_u64 v[148:149], v[148:149], 0, s[16:17]
	s_nop 0
	v_addc_co_u32_e32 v145, vcc, 0, v135, vcc
	v_lshl_add_u64 v[148:149], v[148:149], 0, v[24:25]
	global_load_dwordx4 v[144:147], v[144:145], off
	s_add_i32 s18, s18, 4
	global_load_dwordx4 v[148:151], v[148:149], off
	s_addk_i32 s5, 0x80
	s_add_u32 s20, s20, 0x20000
	s_addc_u32 s21, s21, 0
	s_add_u32 s22, s22, 0x20000
	s_addc_u32 s23, s23, 0
	s_cmp_lt_u32 s18, s3
	s_waitcnt vmcnt(19)
	v_lshlrev_b32_e32 v60, 16, v12
	v_lshlrev_b32_e32 v61, 16, v14
	s_waitcnt vmcnt(18)
	v_lshlrev_b32_e32 v68, 16, v9
	v_and_b32_e32 v70, 0xffff0000, v9
	v_lshlrev_b32_e32 v64, 16, v8
	v_and_b32_e32 v66, 0xffff0000, v8
	v_lshlrev_b32_e32 v65, 16, v10
	v_and_b32_e32 v67, 0xffff0000, v10
	v_lshlrev_b32_e32 v69, 16, v11
	v_and_b32_e32 v71, 0xffff0000, v11
	v_and_b32_e32 v12, 0xffff0000, v12
	v_and_b32_e32 v14, 0xffff0000, v14
	v_lshlrev_b32_e32 v62, 16, v13
	v_lshlrev_b32_e32 v63, 16, v15
	v_and_b32_e32 v13, 0xffff0000, v13
	v_and_b32_e32 v15, 0xffff0000, v15
	s_waitcnt vmcnt(17)
	v_and_b32_e32 v9, 0xffff0000, v20
	v_lshlrev_b32_e32 v8, 16, v20
	v_mul_f32_e32 v72, v9, v9
	v_lshlrev_b32_e32 v10, 16, v21
	v_fmac_f32_e32 v72, v8, v8
	v_and_b32_e32 v11, 0xffff0000, v21
	s_waitcnt vmcnt(16)
	v_lshlrev_b32_e32 v73, 16, v16
	v_and_b32_e32 v16, 0xffff0000, v16
	v_mul_f32_e32 v77, v16, v16
	v_fmac_f32_e32 v72, v10, v10
	v_lshlrev_b32_e32 v20, 16, v22
	v_lshlrev_b32_e32 v74, 16, v17
	v_fmac_f32_e32 v77, v73, v73
	v_fmac_f32_e32 v72, v11, v11
	v_and_b32_e32 v21, 0xffff0000, v22
	v_and_b32_e32 v17, 0xffff0000, v17
	v_fmac_f32_e32 v77, v74, v74
	v_fmac_f32_e32 v72, v20, v20
	s_waitcnt vmcnt(15)
	v_lshlrev_b32_e32 v78, 16, v44
	v_and_b32_e32 v44, 0xffff0000, v44
	v_lshlrev_b32_e32 v22, 16, v23
	v_lshlrev_b32_e32 v75, 16, v18
	v_fmac_f32_e32 v77, v17, v17
	v_mul_f32_e32 v86, v44, v44
	v_fmac_f32_e32 v72, v21, v21
	v_and_b32_e32 v23, 0xffff0000, v23
	v_and_b32_e32 v18, 0xffff0000, v18
	v_lshlrev_b32_e32 v79, 16, v45
	v_fmac_f32_e32 v77, v75, v75
	v_fmac_f32_e32 v86, v78, v78
	v_fmac_f32_e32 v72, v22, v22
	v_lshlrev_b32_e32 v76, 16, v19
	v_and_b32_e32 v45, 0xffff0000, v45
	v_fmac_f32_e32 v77, v18, v18
	v_fmac_f32_e32 v86, v79, v79
	v_fmac_f32_e32 v72, v23, v23
	v_and_b32_e32 v19, 0xffff0000, v19
	v_lshlrev_b32_e32 v80, 16, v46
	v_fmac_f32_e32 v77, v76, v76
	v_fmac_f32_e32 v86, v45, v45
	ds_bpermute_b32 v91, v38, v72
	v_and_b32_e32 v46, 0xffff0000, v46
	v_fmac_f32_e32 v77, v19, v19
	v_fmac_f32_e32 v86, v80, v80
	v_lshlrev_b32_e32 v81, 16, v47
	ds_bpermute_b32 v92, v38, v77
	v_fmac_f32_e32 v86, v46, v46
	v_and_b32_e32 v47, 0xffff0000, v47
	v_fmac_f32_e32 v86, v81, v81
	s_waitcnt vmcnt(12)
	v_lshlrev_b32_e32 v93, 16, v56
	v_and_b32_e32 v56, 0xffff0000, v56
	v_fmac_f32_e32 v86, v47, v47
	v_mul_f32_e32 v97, v56, v56
	ds_bpermute_b32 v98, v38, v86
	s_waitcnt lgkmcnt(2)
	v_add_f32_e32 v72, v72, v91
	v_lshlrev_b32_e32 v94, 16, v57
	v_fmac_f32_e32 v97, v93, v93
	ds_bpermute_b32 v91, v39, v72
	v_and_b32_e32 v57, 0xffff0000, v57
	v_fmac_f32_e32 v97, v94, v94
	s_waitcnt lgkmcnt(2)
	v_add_f32_e32 v77, v77, v92
	v_lshlrev_b32_e32 v95, 16, v58
	v_fmac_f32_e32 v97, v57, v57
	ds_bpermute_b32 v92, v39, v77
	v_and_b32_e32 v58, 0xffff0000, v58
	v_fmac_f32_e32 v97, v95, v95
	v_lshlrev_b32_e32 v96, 16, v59
	v_fmac_f32_e32 v97, v58, v58
	s_waitcnt lgkmcnt(2)
	v_add_f32_e32 v86, v86, v98
	v_and_b32_e32 v59, 0xffff0000, v59
	v_fmac_f32_e32 v97, v96, v96
	ds_bpermute_b32 v98, v39, v86
	s_waitcnt lgkmcnt(2)
	v_add_f32_e32 v72, v72, v91
	v_fmac_f32_e32 v97, v59, v59
	ds_bpermute_b32 v99, v40, v72
	ds_bpermute_b32 v91, v38, v97
	s_waitcnt lgkmcnt(3)
	v_add_f32_e32 v77, v77, v92
	ds_bpermute_b32 v92, v40, v77
	s_waitcnt lgkmcnt(3)
	v_add_f32_e32 v86, v86, v98
	ds_bpermute_b32 v98, v40, v86
	s_waitcnt lgkmcnt(3)
	v_add_f32_e32 v72, v72, v99
	s_waitcnt lgkmcnt(2)
	v_add_f32_e32 v91, v97, v91
	ds_bpermute_b32 v99, v41, v72
	ds_bpermute_b32 v97, v39, v91
	s_waitcnt lgkmcnt(3)
	v_add_f32_e32 v77, v77, v92
	ds_bpermute_b32 v92, v41, v77
	s_waitcnt lgkmcnt(3)
	v_add_f32_e32 v86, v86, v98
	ds_bpermute_b32 v98, v41, v86
	s_waitcnt lgkmcnt(3)
	v_add_f32_e32 v72, v72, v99
	s_waitcnt lgkmcnt(2)
	v_add_f32_e32 v91, v91, v97
	v_fmamk_f32 v72, v72, 0x3c000000, v42
	ds_bpermute_b32 v97, v40, v91
	s_waitcnt lgkmcnt(2)
	v_add_f32_e32 v77, v77, v92
	v_mul_f32_e32 v92, 0x4f800000, v72
	v_cmp_gt_f32_e32 vcc, s19, v72
	v_fmamk_f32 v77, v77, 0x3c000000, v42
	v_cmp_gt_f32_e64 s[8:9], s19, v77
	v_cndmask_b32_e32 v72, v72, v92, vcc
	v_mul_f32_e32 v92, 0x4f800000, v77
	v_sqrt_f32_e32 v99, v72
	v_cndmask_b32_e64 v77, v77, v92, s[8:9]
	s_waitcnt lgkmcnt(1)
	v_add_f32_e32 v86, v86, v98
	v_sqrt_f32_e32 v92, v77
	v_fmamk_f32 v86, v86, 0x3c000000, v42
	s_waitcnt lgkmcnt(0)
	v_add_f32_e32 v91, v91, v97
	v_mul_f32_e32 v97, 0x4f800000, v86
	v_cmp_gt_f32_e64 s[10:11], s19, v86
	ds_bpermute_b32 v98, v41, v91
	v_add_u32_e32 v100, 1, v99
	v_cndmask_b32_e64 v86, v86, v97, s[10:11]
	v_add_u32_e32 v97, -1, v99
	v_sqrt_f32_e32 v101, v86
	v_fma_f32 v102, -v97, v99, v72
	v_fma_f32 v103, -v100, v99, v72
	v_add_u32_e32 v104, -1, v92
	v_cmp_ge_f32_e64 s[12:13], 0, v102
	v_add_u32_e32 v105, 1, v92
	v_fma_f32 v102, -v105, v92, v77
	v_cndmask_b32_e64 v97, v99, v97, s[12:13]
	v_fma_f32 v99, -v104, v92, v77
	v_cmp_lt_f32_e64 s[12:13], 0, v103
	s_waitcnt lgkmcnt(0)
	v_add_f32_e32 v91, v91, v98
	v_fmamk_f32 v91, v91, 0x3c000000, v42
	v_cndmask_b32_e64 v97, v97, v100, s[12:13]
	v_cmp_ge_f32_e64 s[12:13], 0, v99
	v_mul_f32_e32 v98, 0x37800000, v97
	v_add_u32_e32 v99, -1, v101
	v_cndmask_b32_e64 v92, v92, v104, s[12:13]
	v_cmp_lt_f32_e64 s[12:13], 0, v102
	v_add_u32_e32 v100, 1, v101
	v_cndmask_b32_e32 v97, v97, v98, vcc
	v_cndmask_b32_e64 v92, v92, v105, s[12:13]
	v_fma_f32 v102, -v99, v101, v86
	v_cmp_class_f32_e64 s[12:13], v72, v43
	v_mul_f32_e32 v98, 0x37800000, v92
	v_fma_f32 v103, -v100, v101, v86
	v_mul_f32_e32 v104, 0x4f800000, v91
	v_cmp_gt_f32_e32 vcc, s19, v91
	v_cndmask_b32_e64 v72, v97, v72, s[12:13]
	v_cmp_ge_f32_e64 s[12:13], 0, v102
	v_cndmask_b32_e64 v92, v92, v98, s[8:9]
	v_cmp_class_f32_e64 s[8:9], v77, v43
	v_cndmask_b32_e64 v97, v101, v99, s[12:13]
	v_cmp_lt_f32_e64 s[12:13], 0, v103
	v_cndmask_b32_e32 v91, v91, v104, vcc
	v_cndmask_b32_e64 v77, v92, v77, s[8:9]
	v_cndmask_b32_e64 v92, v97, v100, s[12:13]
	v_sqrt_f32_e32 v97, v91
	v_div_scale_f32 v98, s[14:15], v72, v72, 1.0
	v_rcp_f32_e32 v100, v98
	v_div_scale_f32 v101, s[8:9], v77, v77, 1.0
	v_mul_f32_e32 v103, 0x37800000, v92
	v_rcp_f32_e32 v104, v101
	v_cndmask_b32_e64 v92, v92, v103, s[10:11]
	v_cmp_class_f32_e64 s[8:9], v86, v43
	v_add_u32_e32 v105, -1, v97
	v_add_u32_e32 v106, 1, v97
	v_cndmask_b32_e64 v86, v92, v86, s[8:9]
	v_div_scale_f32 v92, s[8:9], v86, v86, 1.0
	v_fma_f32 v109, -v105, v97, v91
	v_fma_f32 v107, -v98, v100, 1.0
	v_rcp_f32_e32 v108, v92
	v_fma_f32 v110, -v106, v97, v91
	v_cmp_ge_f32_e64 s[8:9], 0, v109
	v_div_scale_f32 v99, s[14:15], 1.0, v72, 1.0
	v_fmac_f32_e32 v100, v107, v100
	v_fma_f32 v107, -v101, v104, 1.0
	v_cndmask_b32_e64 v97, v97, v105, s[8:9]
	v_cmp_lt_f32_e64 s[8:9], 0, v110
	v_div_scale_f32 v102, s[12:13], 1.0, v77, 1.0
	v_mul_f32_e32 v105, v99, v100
	v_fmac_f32_e32 v104, v107, v104
	v_cndmask_b32_e64 v97, v97, v106, s[8:9]
	v_fma_f32 v106, -v98, v105, v99
	v_mul_f32_e32 v107, v102, v104
	v_mul_f32_e32 v109, 0x37800000, v97
	v_fmac_f32_e32 v105, v106, v100
	v_fma_f32 v106, -v101, v107, v102
	v_fma_f32 v110, -v92, v108, 1.0
	v_cndmask_b32_e32 v97, v97, v109, vcc
	v_cmp_class_f32_e32 vcc, v91, v43
	v_div_scale_f32 v103, s[10:11], 1.0, v86, 1.0
	v_fma_f32 v98, -v98, v105, v99
	v_fmac_f32_e32 v107, v106, v104
	v_fmac_f32_e32 v108, v110, v108
	v_cndmask_b32_e32 v91, v97, v91, vcc
	s_mov_b64 vcc, s[14:15]
	v_div_fmas_f32 v97, v98, v100, v105
	v_fma_f32 v98, -v101, v107, v102
	v_mul_f32_e32 v99, v103, v108
	v_div_scale_f32 v100, s[8:9], v91, v91, 1.0
	s_mov_b64 vcc, s[12:13]
	v_div_fixup_f32 v72, v97, v72, 1.0
	v_div_fmas_f32 v97, v98, v104, v107
	v_fma_f32 v98, -v92, v99, v103
	v_rcp_f32_e32 v102, v100
	v_mul_f32_e32 v8, v72, v8
	v_mul_f32_e32 v20, v72, v20
	v_mul_f32_e32 v9, v72, v9
	v_mul_f32_e32 v21, v72, v21
	v_mul_f32_e32 v10, v72, v10
	v_mul_f32_e32 v22, v72, v22
	v_mul_f32_e32 v11, v72, v11
	v_mul_f32_e32 v23, v72, v23
	v_div_fixup_f32 v72, v97, v77, 1.0
	v_fmac_f32_e32 v99, v98, v108
	v_mul_f32_e32 v8, v0, v8
	v_mul_f32_e32 v20, v4, v20
	v_mul_f32_e32 v9, v1, v9
	v_mul_f32_e32 v21, v5, v21
	v_mul_f32_e32 v10, v2, v10
	v_mul_f32_e32 v22, v6, v22
	v_mul_f32_e32 v11, v3, v11
	v_mul_f32_e32 v23, v7, v23
	v_mul_f32_e32 v73, v72, v73
	v_mul_f32_e32 v75, v72, v75
	v_mul_f32_e32 v16, v72, v16
	v_mul_f32_e32 v18, v72, v18
	v_mul_f32_e32 v74, v72, v74
	v_mul_f32_e32 v76, v72, v76
	v_mul_f32_e32 v17, v72, v17
	v_mul_f32_e32 v19, v72, v19
	v_fma_f32 v72, -v92, v99, v103
	s_mov_b64 vcc, s[10:11]
	v_mul_f32_e32 v8, v8, v60
	v_mul_f32_e32 v20, v20, v61
	v_mul_f32_e32 v9, v9, v12
	v_mul_f32_e32 v12, v21, v14
	v_mul_f32_e32 v10, v10, v62
	v_mul_f32_e32 v14, v22, v63
	v_mul_f32_e32 v11, v11, v13
	v_mul_f32_e32 v13, v23, v15
	v_mul_f32_e32 v15, v0, v73
	v_mul_f32_e32 v21, v4, v75
	v_mul_f32_e32 v16, v1, v16
	v_mul_f32_e32 v18, v5, v18
	v_mul_f32_e32 v22, v2, v74
	v_mul_f32_e32 v23, v6, v76
	v_mul_f32_e32 v17, v3, v17
	v_mul_f32_e32 v19, v7, v19
	v_div_fmas_f32 v60, v72, v108, v99
	v_cvt_pk_bf16_f32 v8, v8, v9
	v_cvt_pk_bf16_f32 v9, v10, v11
	v_cvt_pk_bf16_f32 v10, v20, v12
	v_cvt_pk_bf16_f32 v11, v14, v13
	v_mul_f32_e32 v12, v15, v64
	v_mul_f32_e32 v13, v21, v65
	v_mul_f32_e32 v14, v16, v66
	v_mul_f32_e32 v15, v18, v67
	v_mul_f32_e32 v16, v22, v68
	v_mul_f32_e32 v18, v23, v69
	v_mul_f32_e32 v17, v17, v70
	v_mul_f32_e32 v19, v19, v71
	v_div_fixup_f32 v20, v60, v86, 1.0
	v_fma_f32 v21, -v100, v102, 1.0
	v_div_scale_f32 v101, s[8:9], 1.0, v91, 1.0
	global_store_dwordx4 v[28:29], v[8:11], off
	v_fmac_f32_e32 v102, v21, v102
	v_lshlrev_b32_e32 v82, 16, v48
	v_cvt_pk_bf16_f32 v8, v12, v14
	v_cvt_pk_bf16_f32 v9, v16, v17
	v_cvt_pk_bf16_f32 v10, v13, v15
	v_cvt_pk_bf16_f32 v11, v18, v19
	v_mul_f32_e32 v12, v20, v78
	v_mul_f32_e32 v13, v20, v80
	v_mul_f32_e32 v14, v20, v44
	v_mul_f32_e32 v15, v20, v46
	v_mul_f32_e32 v16, v20, v79
	v_mul_f32_e32 v17, v20, v81
	v_mul_f32_e32 v18, v20, v45
	v_mul_f32_e32 v19, v20, v47
	v_lshlrev_b32_e32 v83, 16, v50
	v_and_b32_e32 v48, 0xffff0000, v48
	v_and_b32_e32 v50, 0xffff0000, v50
	v_lshlrev_b32_e32 v84, 16, v49
	v_lshlrev_b32_e32 v85, 16, v51
	v_and_b32_e32 v49, 0xffff0000, v49
	v_and_b32_e32 v51, 0xffff0000, v51
	global_store_dwordx4 v[30:31], v[8:11], off
	s_mov_b64 vcc, s[8:9]
	v_lshlrev_b32_e32 v87, 16, v52
	v_mul_f32_e32 v8, v0, v12
	v_mul_f32_e32 v9, v4, v13
	v_mul_f32_e32 v10, v1, v14
	v_mul_f32_e32 v11, v5, v15
	v_mul_f32_e32 v12, v2, v16
	v_mul_f32_e32 v13, v6, v17
	v_mul_f32_e32 v14, v3, v18
	v_mul_f32_e32 v15, v7, v19
	v_mul_f32_e32 v16, v101, v102
	v_mul_f32_e32 v8, v8, v82
	v_mul_f32_e32 v17, v9, v83
	v_mul_f32_e32 v9, v10, v48
	v_mul_f32_e32 v10, v11, v50
	v_mul_f32_e32 v11, v12, v84
	v_mul_f32_e32 v12, v13, v85
	v_mul_f32_e32 v13, v14, v49
	v_mul_f32_e32 v14, v15, v51
	v_fma_f32 v15, -v100, v16, v101
	v_cvt_pk_bf16_f32 v8, v8, v9
	v_fmac_f32_e32 v16, v15, v102
	v_cvt_pk_bf16_f32 v9, v11, v13
	v_cvt_pk_bf16_f32 v10, v17, v10
	v_cvt_pk_bf16_f32 v11, v12, v14
	global_store_dwordx4 v[32:33], v[8:11], off
	v_lshlrev_b32_e32 v88, 16, v54
	v_and_b32_e32 v52, 0xffff0000, v52
	v_fma_f32 v8, -v100, v16, v101
	v_div_fmas_f32 v8, v8, v102, v16
	v_div_fixup_f32 v8, v8, v91, 1.0
	v_mul_f32_e32 v9, v8, v93
	v_mul_f32_e32 v10, v8, v95
	v_mul_f32_e32 v11, v8, v56
	v_add_co_u32_e32 v12, vcc, s4, v34
	v_mul_f32_e32 v14, v8, v58
	v_mul_f32_e32 v15, v8, v94
	v_mul_f32_e32 v16, v8, v96
	v_mul_f32_e32 v17, v8, v57
	v_mul_f32_e32 v8, v8, v59
	v_mul_f32_e32 v9, v0, v9
	v_mul_f32_e32 v10, v4, v10
	v_mul_f32_e32 v11, v1, v11
	v_and_b32_e32 v54, 0xffff0000, v54
	v_lshlrev_b32_e32 v89, 16, v53
	v_lshlrev_b32_e32 v90, 16, v55
	v_and_b32_e32 v53, 0xffff0000, v53
	v_and_b32_e32 v55, 0xffff0000, v55
	v_addc_co_u32_e32 v13, vcc, 0, v35, vcc
	v_mul_f32_e32 v14, v5, v14
	v_mul_f32_e32 v15, v2, v15
	v_mul_f32_e32 v16, v6, v16
	v_mul_f32_e32 v17, v3, v17
	v_mul_f32_e32 v8, v7, v8
	v_mul_f32_e32 v9, v9, v87
	v_mul_f32_e32 v10, v10, v88
	v_mul_f32_e32 v11, v11, v52
	v_mul_f32_e32 v14, v14, v54
	v_mul_f32_e32 v15, v15, v89
	v_mul_f32_e32 v16, v16, v90
	v_mul_f32_e32 v17, v17, v53
	v_mul_f32_e32 v18, v8, v55
	v_cvt_pk_bf16_f32 v8, v9, v11
	v_cvt_pk_bf16_f32 v9, v15, v17
	v_cvt_pk_bf16_f32 v10, v10, v14
	v_cvt_pk_bf16_f32 v11, v16, v18
	global_store_dwordx4 v[12:13], v[8:11], off
	s_nop 1
	s_waitcnt vmcnt(11)
	v_lshlrev_b32_e32 v152, 16, v116
	v_lshlrev_b32_e32 v153, 16, v118
	s_waitcnt vmcnt(10)
	v_lshlrev_b32_e32 v160, 16, v113
	v_and_b32_e32 v162, 0xffff0000, v113
	v_lshlrev_b32_e32 v156, 16, v112
	v_and_b32_e32 v158, 0xffff0000, v112
	v_lshlrev_b32_e32 v157, 16, v114
	v_and_b32_e32 v159, 0xffff0000, v114
	v_lshlrev_b32_e32 v161, 16, v115
	v_and_b32_e32 v163, 0xffff0000, v115
	v_and_b32_e32 v116, 0xffff0000, v116
	v_and_b32_e32 v118, 0xffff0000, v118
	v_lshlrev_b32_e32 v154, 16, v117
	v_lshlrev_b32_e32 v155, 16, v119
	v_and_b32_e32 v117, 0xffff0000, v117
	v_and_b32_e32 v119, 0xffff0000, v119
	s_waitcnt vmcnt(9)
	v_and_b32_e32 v113, 0xffff0000, v124
	v_lshlrev_b32_e32 v112, 16, v124
	v_mul_f32_e32 v164, v113, v113
	v_lshlrev_b32_e32 v114, 16, v125
	v_fmac_f32_e32 v164, v112, v112
	v_and_b32_e32 v115, 0xffff0000, v125
	s_waitcnt vmcnt(8)
	v_lshlrev_b32_e32 v165, 16, v120
	v_and_b32_e32 v120, 0xffff0000, v120
	v_mul_f32_e32 v169, v120, v120
	v_fmac_f32_e32 v164, v114, v114
	v_lshlrev_b32_e32 v124, 16, v126
	v_lshlrev_b32_e32 v166, 16, v121
	v_fmac_f32_e32 v169, v165, v165
	v_fmac_f32_e32 v164, v115, v115
	v_and_b32_e32 v125, 0xffff0000, v126
	v_and_b32_e32 v121, 0xffff0000, v121
	v_fmac_f32_e32 v169, v166, v166
	v_fmac_f32_e32 v164, v124, v124
	s_waitcnt vmcnt(7)
	v_lshlrev_b32_e32 v170, 16, v136
	v_and_b32_e32 v136, 0xffff0000, v136
	v_lshlrev_b32_e32 v126, 16, v127
	v_lshlrev_b32_e32 v167, 16, v122
	v_fmac_f32_e32 v169, v121, v121
	v_mul_f32_e32 v192, v136, v136
	v_fmac_f32_e32 v164, v125, v125
	v_and_b32_e32 v127, 0xffff0000, v127
	v_and_b32_e32 v122, 0xffff0000, v122
	v_lshlrev_b32_e32 v171, 16, v137
	v_fmac_f32_e32 v169, v167, v167
	v_fmac_f32_e32 v192, v170, v170
	v_fmac_f32_e32 v164, v126, v126
	v_lshlrev_b32_e32 v168, 16, v123
	v_and_b32_e32 v137, 0xffff0000, v137
	v_fmac_f32_e32 v169, v122, v122
	v_fmac_f32_e32 v192, v171, v171
	v_fmac_f32_e32 v164, v127, v127
	v_and_b32_e32 v123, 0xffff0000, v123
	v_lshlrev_b32_e32 v186, 16, v138
	v_fmac_f32_e32 v169, v168, v168
	v_fmac_f32_e32 v192, v137, v137
	ds_bpermute_b32 v197, v38, v164
	v_and_b32_e32 v138, 0xffff0000, v138
	v_fmac_f32_e32 v169, v123, v123
	v_fmac_f32_e32 v192, v186, v186
	v_lshlrev_b32_e32 v187, 16, v139
	ds_bpermute_b32 v198, v38, v169
	v_fmac_f32_e32 v192, v138, v138
	v_and_b32_e32 v139, 0xffff0000, v139
	v_fmac_f32_e32 v192, v187, v187
	s_waitcnt vmcnt(4)
	v_lshlrev_b32_e32 v199, 16, v148
	v_and_b32_e32 v148, 0xffff0000, v148
	v_fmac_f32_e32 v192, v139, v139
	v_mul_f32_e32 v203, v148, v148
	ds_bpermute_b32 v204, v38, v192
	s_waitcnt lgkmcnt(2)
	v_add_f32_e32 v164, v164, v197
	v_lshlrev_b32_e32 v200, 16, v149
	v_fmac_f32_e32 v203, v199, v199
	ds_bpermute_b32 v197, v39, v164
	v_and_b32_e32 v149, 0xffff0000, v149
	v_fmac_f32_e32 v203, v200, v200
	s_waitcnt lgkmcnt(2)
	v_add_f32_e32 v169, v169, v198
	v_lshlrev_b32_e32 v201, 16, v150
	v_fmac_f32_e32 v203, v149, v149
	ds_bpermute_b32 v198, v39, v169
	v_and_b32_e32 v150, 0xffff0000, v150
	v_fmac_f32_e32 v203, v201, v201
	v_lshlrev_b32_e32 v202, 16, v151
	v_fmac_f32_e32 v203, v150, v150
	s_waitcnt lgkmcnt(2)
	v_add_f32_e32 v192, v192, v204
	v_and_b32_e32 v151, 0xffff0000, v151
	v_fmac_f32_e32 v203, v202, v202
	ds_bpermute_b32 v204, v39, v192
	s_waitcnt lgkmcnt(2)
	v_add_f32_e32 v164, v164, v197
	v_fmac_f32_e32 v203, v151, v151
	ds_bpermute_b32 v205, v40, v164
	ds_bpermute_b32 v197, v38, v203
	s_waitcnt lgkmcnt(3)
	v_add_f32_e32 v169, v169, v198
	ds_bpermute_b32 v198, v40, v169
	s_waitcnt lgkmcnt(3)
	v_add_f32_e32 v192, v192, v204
	ds_bpermute_b32 v204, v40, v192
	s_waitcnt lgkmcnt(3)
	v_add_f32_e32 v164, v164, v205
	s_waitcnt lgkmcnt(2)
	v_add_f32_e32 v197, v203, v197
	ds_bpermute_b32 v205, v41, v164
	ds_bpermute_b32 v203, v39, v197
	s_waitcnt lgkmcnt(3)
	v_add_f32_e32 v169, v169, v198
	ds_bpermute_b32 v198, v41, v169
	s_waitcnt lgkmcnt(3)
	v_add_f32_e32 v192, v192, v204
	ds_bpermute_b32 v204, v41, v192
	s_waitcnt lgkmcnt(3)
	v_add_f32_e32 v164, v164, v205
	s_waitcnt lgkmcnt(2)
	v_add_f32_e32 v197, v197, v203
	v_fmamk_f32 v164, v164, 0x3c000000, v42
	ds_bpermute_b32 v203, v40, v197
	s_waitcnt lgkmcnt(2)
	v_add_f32_e32 v169, v169, v198
	v_mul_f32_e32 v198, 0x4f800000, v164
	v_cmp_gt_f32_e32 vcc, s19, v164
	v_fmamk_f32 v169, v169, 0x3c000000, v42
	v_cmp_gt_f32_e64 s[8:9], s19, v169
	v_cndmask_b32_e32 v164, v164, v198, vcc
	v_mul_f32_e32 v198, 0x4f800000, v169
	v_sqrt_f32_e32 v205, v164
	v_cndmask_b32_e64 v169, v169, v198, s[8:9]
	s_waitcnt lgkmcnt(1)
	v_add_f32_e32 v192, v192, v204
	v_sqrt_f32_e32 v198, v169
	v_fmamk_f32 v192, v192, 0x3c000000, v42
	s_waitcnt lgkmcnt(0)
	v_add_f32_e32 v197, v197, v203
	v_mul_f32_e32 v203, 0x4f800000, v192
	v_cmp_gt_f32_e64 s[10:11], s19, v192
	ds_bpermute_b32 v204, v41, v197
	v_add_u32_e32 v206, 1, v205
	v_cndmask_b32_e64 v192, v192, v203, s[10:11]
	v_add_u32_e32 v203, -1, v205
	v_sqrt_f32_e32 v207, v192
	v_fma_f32 v208, -v203, v205, v164
	v_fma_f32 v209, -v206, v205, v164
	v_add_u32_e32 v210, -1, v198
	v_cmp_ge_f32_e64 s[12:13], 0, v208
	v_add_u32_e32 v211, 1, v198
	v_fma_f32 v208, -v211, v198, v169
	v_cndmask_b32_e64 v203, v205, v203, s[12:13]
	v_fma_f32 v205, -v210, v198, v169
	v_cmp_lt_f32_e64 s[12:13], 0, v209
	s_waitcnt lgkmcnt(0)
	v_add_f32_e32 v197, v197, v204
	v_fmamk_f32 v197, v197, 0x3c000000, v42
	v_cndmask_b32_e64 v203, v203, v206, s[12:13]
	v_cmp_ge_f32_e64 s[12:13], 0, v205
	v_mul_f32_e32 v204, 0x37800000, v203
	v_add_u32_e32 v205, -1, v207
	v_cndmask_b32_e64 v198, v198, v210, s[12:13]
	v_cmp_lt_f32_e64 s[12:13], 0, v208
	v_add_u32_e32 v206, 1, v207
	v_cndmask_b32_e32 v203, v203, v204, vcc
	v_cndmask_b32_e64 v198, v198, v211, s[12:13]
	v_fma_f32 v208, -v205, v207, v192
	v_cmp_class_f32_e64 s[12:13], v164, v43
	v_mul_f32_e32 v204, 0x37800000, v198
	v_fma_f32 v209, -v206, v207, v192
	v_mul_f32_e32 v210, 0x4f800000, v197
	v_cmp_gt_f32_e32 vcc, s19, v197
	v_cndmask_b32_e64 v164, v203, v164, s[12:13]
	v_cmp_ge_f32_e64 s[12:13], 0, v208
	v_cndmask_b32_e64 v198, v198, v204, s[8:9]
	v_cmp_class_f32_e64 s[8:9], v169, v43
	v_cndmask_b32_e64 v203, v207, v205, s[12:13]
	v_cmp_lt_f32_e64 s[12:13], 0, v209
	v_cndmask_b32_e32 v197, v197, v210, vcc
	v_cndmask_b32_e64 v169, v198, v169, s[8:9]
	v_cndmask_b32_e64 v198, v203, v206, s[12:13]
	v_sqrt_f32_e32 v203, v197
	v_div_scale_f32 v204, s[14:15], v164, v164, 1.0
	v_rcp_f32_e32 v206, v204
	v_div_scale_f32 v207, s[8:9], v169, v169, 1.0
	v_mul_f32_e32 v209, 0x37800000, v198
	v_rcp_f32_e32 v210, v207
	v_cndmask_b32_e64 v198, v198, v209, s[10:11]
	v_cmp_class_f32_e64 s[8:9], v192, v43
	v_add_u32_e32 v211, -1, v203
	v_add_u32_e32 v212, 1, v203
	v_cndmask_b32_e64 v192, v198, v192, s[8:9]
	v_div_scale_f32 v198, s[8:9], v192, v192, 1.0
	v_fma_f32 v215, -v211, v203, v197
	v_fma_f32 v213, -v204, v206, 1.0
	v_rcp_f32_e32 v214, v198
	v_fma_f32 v216, -v212, v203, v197
	v_cmp_ge_f32_e64 s[8:9], 0, v215
	v_div_scale_f32 v205, s[14:15], 1.0, v164, 1.0
	v_fmac_f32_e32 v206, v213, v206
	v_fma_f32 v213, -v207, v210, 1.0
	v_cndmask_b32_e64 v203, v203, v211, s[8:9]
	v_cmp_lt_f32_e64 s[8:9], 0, v216
	v_div_scale_f32 v208, s[12:13], 1.0, v169, 1.0
	v_mul_f32_e32 v211, v205, v206
	v_fmac_f32_e32 v210, v213, v210
	v_cndmask_b32_e64 v203, v203, v212, s[8:9]
	v_fma_f32 v212, -v204, v211, v205
	v_mul_f32_e32 v213, v208, v210
	v_mul_f32_e32 v215, 0x37800000, v203
	v_fmac_f32_e32 v211, v212, v206
	v_fma_f32 v212, -v207, v213, v208
	v_fma_f32 v216, -v198, v214, 1.0
	v_cndmask_b32_e32 v203, v203, v215, vcc
	v_cmp_class_f32_e32 vcc, v197, v43
	v_div_scale_f32 v209, s[10:11], 1.0, v192, 1.0
	v_fma_f32 v204, -v204, v211, v205
	v_fmac_f32_e32 v213, v212, v210
	v_fmac_f32_e32 v214, v216, v214
	v_cndmask_b32_e32 v197, v203, v197, vcc
	s_mov_b64 vcc, s[14:15]
	v_div_fmas_f32 v203, v204, v206, v211
	v_fma_f32 v204, -v207, v213, v208
	v_mul_f32_e32 v205, v209, v214
	v_div_scale_f32 v206, s[8:9], v197, v197, 1.0
	s_mov_b64 vcc, s[12:13]
	v_div_fixup_f32 v164, v203, v164, 1.0
	v_div_fmas_f32 v203, v204, v210, v213
	v_fma_f32 v204, -v198, v205, v209
	v_rcp_f32_e32 v208, v206
	v_mul_f32_e32 v112, v164, v112
	v_mul_f32_e32 v124, v164, v124
	v_mul_f32_e32 v113, v164, v113
	v_mul_f32_e32 v125, v164, v125
	v_mul_f32_e32 v114, v164, v114
	v_mul_f32_e32 v126, v164, v126
	v_mul_f32_e32 v115, v164, v115
	v_mul_f32_e32 v127, v164, v127
	v_div_fixup_f32 v164, v203, v169, 1.0
	v_fmac_f32_e32 v205, v204, v214
	v_mul_f32_e32 v112, v0, v112
	v_mul_f32_e32 v124, v4, v124
	v_mul_f32_e32 v113, v1, v113
	v_mul_f32_e32 v125, v5, v125
	v_mul_f32_e32 v114, v2, v114
	v_mul_f32_e32 v126, v6, v126
	v_mul_f32_e32 v115, v3, v115
	v_mul_f32_e32 v127, v7, v127
	v_mul_f32_e32 v165, v164, v165
	v_mul_f32_e32 v167, v164, v167
	v_mul_f32_e32 v120, v164, v120
	v_mul_f32_e32 v122, v164, v122
	v_mul_f32_e32 v166, v164, v166
	v_mul_f32_e32 v168, v164, v168
	v_mul_f32_e32 v121, v164, v121
	v_mul_f32_e32 v123, v164, v123
	v_fma_f32 v164, -v198, v205, v209
	s_mov_b64 vcc, s[10:11]
	v_mul_f32_e32 v112, v112, v152
	v_mul_f32_e32 v124, v124, v153
	v_mul_f32_e32 v113, v113, v116
	v_mul_f32_e32 v116, v125, v118
	v_mul_f32_e32 v114, v114, v154
	v_mul_f32_e32 v118, v126, v155
	v_mul_f32_e32 v115, v115, v117
	v_mul_f32_e32 v117, v127, v119
	v_mul_f32_e32 v119, v0, v165
	v_mul_f32_e32 v125, v4, v167
	v_mul_f32_e32 v120, v1, v120
	v_mul_f32_e32 v122, v5, v122
	v_mul_f32_e32 v126, v2, v166
	v_mul_f32_e32 v127, v6, v168
	v_mul_f32_e32 v121, v3, v121
	v_mul_f32_e32 v123, v7, v123
	v_div_fmas_f32 v152, v164, v214, v205
	v_cvt_pk_bf16_f32 v112, v112, v113
	v_cvt_pk_bf16_f32 v113, v114, v115
	v_cvt_pk_bf16_f32 v114, v124, v116
	v_cvt_pk_bf16_f32 v115, v118, v117
	v_mul_f32_e32 v116, v119, v156
	v_mul_f32_e32 v117, v125, v157
	v_mul_f32_e32 v118, v120, v158
	v_mul_f32_e32 v119, v122, v159
	v_mul_f32_e32 v120, v126, v160
	v_mul_f32_e32 v122, v127, v161
	v_mul_f32_e32 v121, v121, v162
	v_mul_f32_e32 v123, v123, v163
	v_div_fixup_f32 v124, v152, v192, 1.0
	v_fma_f32 v125, -v206, v208, 1.0
	v_div_scale_f32 v207, s[8:9], 1.0, v197, 1.0
	global_store_dwordx4 v[128:129], v[112:115], off
	v_fmac_f32_e32 v208, v125, v208
	v_lshlrev_b32_e32 v188, 16, v140
	v_cvt_pk_bf16_f32 v112, v116, v118
	v_cvt_pk_bf16_f32 v113, v120, v121
	v_cvt_pk_bf16_f32 v114, v117, v119
	v_cvt_pk_bf16_f32 v115, v122, v123
	v_mul_f32_e32 v116, v124, v170
	v_mul_f32_e32 v117, v124, v186
	v_mul_f32_e32 v118, v124, v136
	v_mul_f32_e32 v119, v124, v138
	v_mul_f32_e32 v120, v124, v171
	v_mul_f32_e32 v121, v124, v187
	v_mul_f32_e32 v122, v124, v137
	v_mul_f32_e32 v123, v124, v139
	v_lshlrev_b32_e32 v189, 16, v142
	v_and_b32_e32 v140, 0xffff0000, v140
	v_and_b32_e32 v142, 0xffff0000, v142
	v_lshlrev_b32_e32 v190, 16, v141
	v_lshlrev_b32_e32 v191, 16, v143
	v_and_b32_e32 v141, 0xffff0000, v141
	v_and_b32_e32 v143, 0xffff0000, v143
	global_store_dwordx4 v[130:131], v[112:115], off
	s_mov_b64 vcc, s[8:9]
	v_lshlrev_b32_e32 v193, 16, v144
	v_mul_f32_e32 v112, v0, v116
	v_mul_f32_e32 v113, v4, v117
	v_mul_f32_e32 v114, v1, v118
	v_mul_f32_e32 v115, v5, v119
	v_mul_f32_e32 v116, v2, v120
	v_mul_f32_e32 v117, v6, v121
	v_mul_f32_e32 v118, v3, v122
	v_mul_f32_e32 v119, v7, v123
	v_mul_f32_e32 v120, v207, v208
	v_mul_f32_e32 v112, v112, v188
	v_mul_f32_e32 v121, v113, v189
	v_mul_f32_e32 v113, v114, v140
	v_mul_f32_e32 v114, v115, v142
	v_mul_f32_e32 v115, v116, v190
	v_mul_f32_e32 v116, v117, v191
	v_mul_f32_e32 v117, v118, v141
	v_mul_f32_e32 v118, v119, v143
	v_fma_f32 v119, -v206, v120, v207
	v_cvt_pk_bf16_f32 v112, v112, v113
	v_fmac_f32_e32 v120, v119, v208
	v_cvt_pk_bf16_f32 v113, v115, v117
	v_cvt_pk_bf16_f32 v114, v121, v114
	v_cvt_pk_bf16_f32 v115, v116, v118
	global_store_dwordx4 v[132:133], v[112:115], off
	v_lshlrev_b32_e32 v194, 16, v146
	v_and_b32_e32 v144, 0xffff0000, v144
	v_fma_f32 v112, -v206, v120, v207
	v_div_fmas_f32 v112, v112, v208, v120
	v_div_fixup_f32 v112, v112, v197, 1.0
	v_mul_f32_e32 v113, v112, v199
	v_mul_f32_e32 v114, v112, v201
	v_mul_f32_e32 v115, v112, v148
	v_add_co_u32_e32 v116, vcc, s4, v134
	v_mul_f32_e32 v118, v112, v150
	v_mul_f32_e32 v119, v112, v200
	v_mul_f32_e32 v120, v112, v202
	v_mul_f32_e32 v121, v112, v149
	v_mul_f32_e32 v112, v112, v151
	v_mul_f32_e32 v113, v0, v113
	v_mul_f32_e32 v114, v4, v114
	v_mul_f32_e32 v115, v1, v115
	v_and_b32_e32 v146, 0xffff0000, v146
	v_lshlrev_b32_e32 v195, 16, v145
	v_lshlrev_b32_e32 v196, 16, v147
	v_and_b32_e32 v145, 0xffff0000, v145
	v_and_b32_e32 v147, 0xffff0000, v147
	v_addc_co_u32_e32 v117, vcc, 0, v135, vcc
	v_mul_f32_e32 v118, v5, v118
	v_mul_f32_e32 v119, v2, v119
	v_mul_f32_e32 v120, v6, v120
	v_mul_f32_e32 v121, v3, v121
	v_mul_f32_e32 v112, v7, v112
	v_mul_f32_e32 v113, v113, v193
	v_mul_f32_e32 v114, v114, v194
	v_mul_f32_e32 v115, v115, v144
	v_mul_f32_e32 v118, v118, v146
	v_mul_f32_e32 v119, v119, v195
	v_mul_f32_e32 v120, v120, v196
	v_mul_f32_e32 v121, v121, v145
	v_mul_f32_e32 v122, v112, v147
	v_cvt_pk_bf16_f32 v112, v113, v115
	v_cvt_pk_bf16_f32 v113, v119, v121
	v_cvt_pk_bf16_f32 v114, v114, v118
	v_cvt_pk_bf16_f32 v115, v120, v122
	global_store_dwordx4 v[116:117], v[112:115], off
	s_nop 1
